# fox stagger: waves 4-7 rendezvous mid-tile, 4 LDS stages, waves 0-3 stage K/V; T=80
# speedup vs baseline: 1.0621x; 1.0089x over previous
; DI void fox_unit(const Params& p, int hf, int bl, int fh, int qb, unsigned char* shm, int tid, bool dry = false) {
;     ...
;   const float kmax2 = ((const float*)(wsb + WS_KMAX))[bl * 8 + fh];
;   const float thr = -110.0f - 0.25f * sqrtf(qm2 * kmax2) * 1.02f;
;   const int nkt = 4 * qb + 4;
;   int skip = 0;
;   if (tid < 4 * qb) skip = (Fref - F[tid * 64 + 63] < thr) ? 1 : 0;
;   const unsigned long long bal = __builtin_amdgcn_ballot_w64(skip != 0);
;   if (lane == 0) ((int*)sRed)[8 + wid] = __builtin_popcountll(bal);
;   __syncthreads();
;   int kt0 = 0;
; #pragma unroll
;   for (int i = 0; i < 8; ++i) kt0 += ((const int*)sRed)[8 + i];
;   f32x4 o[2][4];
; #pragma unroll
;   for (int mi = 0; mi < 2; ++mi)
; #pragma unroll
;     for (int d = 0; d < 4; ++d) o[mi][d] = (f32x4){0.f, 0.f, 0.f, 0.f};
;   float mrun[2] = {-1e30f, -1e30f}, lsum[2] = {0.f, 0.f};
;   const int skey = tid >> 3, sdg = tid & 7;
;   const int kst = ((skey >> 4) * 2 + (sdg >> 2)) * 1024 + ((((skey & 15) * 64) + (sdg & 3) * 16) ^ (((skey >> 3) & 1) << 5));
;   uint4 kreg, vreg; float freg = 0.f;
;   {
;     const size_t r = (size_t)(kt0 * 64 + skey) * NP;
;     kreg = *(const uint4*)(projb + r + C_FK + fh * 64 + sdg * 8); vreg = *(const uint4*)(projb + r + C_FV + fh * 64 + sdg * 8);
;     if (tid < 64) freg = (Fref - F[kt0 * 64 + tid]) * LOG2E;
;   }
;   {
;     bf16_t* sK = (bf16_t*)(shm + (kt0 & 1) * STG); bf16_t* sV = sK + 64 * 72; float* sFk = (float*)(sV + 64 * 72);
;     *(uint4*)((unsigned char*)sK + kst) = kreg; *(uint4*)(sV + skey * 72 + sdg * 8) = vreg;
;     if (tid < 64) sFk[tid] = freg;
;   }
;   __syncthreads();
.LBB0_473:
	s_or_b64 exec, exec, s[10:11]
	v_cndmask_b32_e64 v17, 0, 1, s[4:5]
	v_cmp_ne_u32_e64 s[0:1], 0, v17
	s_and_saveexec_b64 s[4:5], vcc
	s_bcnt1_i32_b64 s0, s[0:1]
	v_mov_b32_e32 v17, s0
	ds_write_b32 v16, v17 offset:37408
	s_or_b64 exec, exec, s[4:5]
	s_waitcnt lgkmcnt(0)
	s_barrier
	ds_read_b128 v[16:19], v203 offset:37408
	ds_read_b128 v[20:23], v203 offset:37424
	v_ashrrev_i32_e32 v25, 3, v205
	v_and_b32_e32 v29, 7, v205
	v_lshlrev_b32_e32 v160, 4, v29
	s_waitcnt lgkmcnt(1)
	v_readfirstlane_b32 s0, v16
	v_readfirstlane_b32 s1, v17
	v_readfirstlane_b32 s4, v18
	s_add_i32 s0, s1, s0
	v_readfirstlane_b32 s5, v19
	s_add_i32 s0, s0, s4
	s_waitcnt lgkmcnt(0)
	s_barrier
	v_readfirstlane_b32 s10, v20
	s_add_i32 s0, s0, s5
	v_readfirstlane_b32 s11, v21
	s_add_i32 s0, s0, s10
	v_readfirstlane_b32 s12, v22
	s_add_i32 s0, s0, s11
	v_readfirstlane_b32 s13, v23
	s_add_i32 s0, s0, s12
	s_add_i32 s22, s0, s13
	s_lshl_b32 s18, s22, 6
	v_add_u32_e32 v18, s18, v25
	v_mov_b64_e32 v[16:17], s[6:7]
	v_mad_i64_i32 v[16:17], s[0:1], v18, s65, v[16:17]
	v_lshl_add_u64 v[16:17], v[16:17], 0, s[2:3]
	v_lshl_add_u64 v[16:17], v[16:17], 0, v[160:161]
	v_add_co_u32_e32 v18, vcc, 0x1000, v16
	v_cmp_gt_i32_e64 s[0:1], 64, v205
	s_nop 0
	v_addc_co_u32_e32 v19, vcc, 0, v17, vcc
	v_add_co_u32_e32 v20, vcc, 0x2000, v16
	v_mov_b32_e32 v208, 0
	s_nop 0
	v_addc_co_u32_e32 v21, vcc, 0, v17, vcc
	global_load_dwordx4 v[16:19], v[18:19], off offset:3072
	s_nop 0
	global_load_dwordx4 v[20:23], v[20:21], off
	s_and_saveexec_b64 s[4:5], s[0:1]
	s_cbranch_execz .LBB0_477
	v_add_u32_e32 v30, s18, v205
	v_ashrrev_i32_e32 v31, 31, v30
	v_lshl_add_u64 v[30:31], v[30:31], 2, s[8:9]
	global_load_dword v30, v[30:31], off
	s_waitcnt vmcnt(0)
	v_sub_f32_e32 v30, v192, v30
	v_mul_f32_e32 v208, 0x3fb8aa3b, v30
.LBB0_477:
	s_or_b64 exec, exec, s[4:5]
	v_lshlrev_b32_e32 v30, 3, v29
	v_lshrrev_b32_e32 v29, 2, v29
	s_mov_b32 s4, 0x3ffffe
	v_lshlrev_b32_e32 v31, 4, v205
	v_and_or_b32 v26, v26, s4, v29
	v_lshlrev_b32_e32 v29, 6, v25
	v_and_b32_e32 v31, 48, v31
	s_movk_i32 s4, 0x3c0
	v_and_or_b32 v29, v29, s4, v31
	v_lshrrev_b32_e32 v31, 1, v205
	s_and_b32 s4, s22, 3
	v_lshlrev_b32_e32 v26, 10, v26
	v_and_b32_e32 v31, 32, v31
	s_mulk_i32 s4, 0x4900
	v_bitop3_b32 v210, v29, v26, v31 bitop3:0xde
	s_add_i32 s10, s4, 32
	v_add_u32_e32 v26, s10, v210
	s_movk_i32 s4, 0x48
	s_waitcnt vmcnt(1)
	ds_write_b128 v26, v[16:19]
	v_mul_lo_u32 v26, v25, s4
	v_lshlrev_b32_e32 v211, 1, v26
	v_lshlrev_b32_e32 v160, 1, v30
	v_add3_u32 v26, s10, v211, v160
	s_waitcnt vmcnt(0)
	ds_write_b128 v26, v[20:23] offset:9216
	s_and_saveexec_b64 s[4:5], s[0:1]
	v_lshl_add_u32 v26, v205, 2, s10
	ds_write_b32 v26, v208 offset:18432
	s_or_b64 exec, exec, s[4:5]
	v_bfe_u32 v29, v205, 4, 2
	s_add_i32 s19, s17, 4
	s_mov_b64 s[4:5], -1
	s_cmp_lt_i32 s22, s19
	v_lshlrev_b32_e32 v209, 2, v29
	s_waitcnt lgkmcnt(0)
	s_barrier
	s_cbranch_scc1 .LBB0_481
	v_lshlrev_b32_e32 v26, 2, v29
	s_mov_b64 s[4:5], 0
; DI void fox_unit(const Params& p, int hf, int bl, int fh, int qb, unsigned char* shm, int tid, bool dry = false) {
;     ...
;   f32x4 o[2][4];
; #pragma unroll
;   for (int mi = 0; mi < 2; ++mi)
; #pragma unroll
;     for (int d = 0; d < 4; ++d) o[mi][d] = (f32x4){0.f, 0.f, 0.f, 0.f};
;   float mrun[2] = {-1e30f, -1e30f}, lsum[2] = {0.f, 0.f};
;   const int skey = tid >> 3, sdg = tid & 7;
;   const int kst = ((skey >> 4) * 2 + (sdg >> 2)) * 1024 + ((((skey & 15) * 64) + (sdg & 3) * 16) ^ (((skey >> 3) & 1) << 5));
;   uint4 kreg, vreg; float freg = 0.f;
;   {
;     const size_t r = (size_t)(kt0 * 64 + skey) * NP;
;     kreg = *(const uint4*)(projb + r + C_FK + fh * 64 + sdg * 8); vreg = *(const uint4*)(projb + r + C_FV + fh * 64 + sdg * 8);
;     if (tid < 64) freg = (Fref - F[kt0 * 64 + tid]) * LOG2E;
;   }
;   {
;     bf16_t* sK = (bf16_t*)(shm + (kt0 & 1) * STG); bf16_t* sV = sK + 64 * 72; float* sFk = (float*)(sV + 64 * 72);
;     *(uint4*)((unsigned char*)sK + kst) = kreg; *(uint4*)(sV + skey * 72 + sdg * 8) = vreg;
;     if (tid < 64) sFk[tid] = freg;
;   }
;   __syncthreads();
;   for (int kt = kt0; kt < nkt; ++kt) {
;     const int st = kt & 1;
;     if (kt + 1 < nkt) {
;       const size_t r = (size_t)((kt + 1) * 64 + skey) * NP;
;       kreg = *(const uint4*)(projb + r + C_FK + fh * 64 + sdg * 8); vreg = *(const uint4*)(projb + r + C_FV + fh * 64 + sdg * 8);
;       if (tid < 64) freg = (Fref - F[(kt + 1) * 64 + tid]) * LOG2E;
;     }
;     const bf16_t* sK = (const bf16_t*)(shm + st * STG); const bf16_t* sV = sK + 64 * 72; const float* sFk = (const float*)(sV + 64 * 72);
;     if (kt * 64 <= q0 + wid * 32 + 31) {
.LBB0_481:
	v_mov_b32_e32 v129, 0
	s_andn2_b64 vcc, exec, s[4:5]
	v_mov_b32_e32 v128, v129
	v_mov_b32_e32 v143, v129
	v_mov_b32_e32 v142, v129
	v_mov_b32_e32 v145, v129
	v_mov_b32_e32 v144, v129
	v_mov_b32_e32 v139, v129
	v_mov_b32_e32 v138, v129
	v_mov_b32_e32 v141, v129
	v_mov_b32_e32 v140, v129
	v_mov_b32_e32 v135, v129
	v_mov_b32_e32 v134, v129
	v_mov_b32_e32 v137, v129
	v_mov_b32_e32 v136, v129
	v_mov_b32_e32 v131, v129
	v_mov_b32_e32 v130, v129
	v_mov_b32_e32 v133, v129
	v_mov_b32_e32 v132, v129
	v_mov_b32_e32 v123, v129
	v_mov_b32_e32 v122, v129
	v_mov_b32_e32 v125, v129
	v_mov_b32_e32 v124, v129
	v_mov_b32_e32 v119, v129
	v_mov_b32_e32 v118, v129
	v_mov_b32_e32 v121, v129
	v_mov_b32_e32 v120, v129
	v_mov_b32_e32 v115, v129
	v_mov_b32_e32 v114, v129
	v_mov_b32_e32 v117, v129
	v_mov_b32_e32 v116, v129
	v_mov_b32_e32 v111, v129
	v_mov_b32_e32 v110, v129
	v_mov_b32_e32 v113, v129
	v_mov_b32_e32 v112, v129
	s_cbranch_vccnz .LBB0_635
	v_or_b32_e32 v212, 31, v28
	v_lshlrev_b32_e32 v28, 2, v27
	v_lshlrev_b32_e32 v26, 6, v27
	v_and_b32_e32 v29, 32, v28
	v_bitop3_b32 v213, v26, v29, v24 bitop3:0x36
	v_lshrrev_b32_e32 v24, 2, v27
	v_or_b32_e32 v24, v209, v24
	v_mov_b32_e32 v112, 0
	v_and_b32_e32 v214, 12, v28
	v_mul_u32_u24_e32 v215, 0x90, v24
	v_add_u32_e32 v216, 64, v205
	v_add_u32_e32 v217, 64, v25
	v_readfirstlane_b32 s99, v205
	s_nop 3
	s_lshr_b32 s99, s99, 8
	v_mov_b32_e32 v219, 0xf149f2ca
	v_mov_b32_e32 v113, v112
	v_mov_b32_e32 v110, v112
	v_mov_b32_e32 v111, v112
	v_mov_b32_e32 v116, v112
	v_mov_b32_e32 v117, v112
	v_mov_b32_e32 v114, v112
	v_mov_b32_e32 v115, v112
	v_mov_b32_e32 v120, v112
	v_mov_b32_e32 v121, v112
	v_mov_b32_e32 v118, v112
	v_mov_b32_e32 v119, v112
	v_mov_b32_e32 v124, v112
	v_mov_b32_e32 v125, v112
	v_mov_b32_e32 v122, v112
	v_mov_b32_e32 v123, v112
	v_mov_b32_e32 v132, v112
	v_mov_b32_e32 v133, v112
	v_mov_b32_e32 v130, v112
	v_mov_b32_e32 v131, v112
	v_mov_b32_e32 v136, v112
	v_mov_b32_e32 v137, v112
	v_mov_b32_e32 v134, v112
	v_mov_b32_e32 v135, v112
	v_mov_b32_e32 v140, v112
	v_mov_b32_e32 v141, v112
	v_mov_b32_e32 v138, v112
	v_mov_b32_e32 v139, v112
	v_mov_b32_e32 v144, v112
	v_mov_b32_e32 v145, v112
	v_mov_b32_e32 v142, v112
	v_mov_b32_e32 v143, v112
	v_mov_b32_e32 v128, v112
	v_mov_b32_e32 v129, v112
	v_mov_b32_e32 v218, 0xf149f2ca
	v_mov_b32_e32 v224, 0x7149f2ca
	v_mov_b32_e32 v225, v224
	v_mov_b32_e32 v226, v224
	v_mov_b32_e32 v227, v224
	v_mov_b32_e32 v228, v224
	v_mov_b32_e32 v229, v224
	v_mov_b32_e32 v230, v224
	v_mov_b32_e32 v231, v224
.LBB0_483:
	s_add_i32 s20, s22, 1
	s_cmp_lt_i32 s20, s19
	s_cselect_b64 s[12:13], -1, 0
	s_cmp_ge_i32 s20, s19
	s_cselect_b64 s[10:11], -1, 0
	s_and_b64 vcc, exec, s[10:11]
	s_cbranch_vccz .LBB0_486
	s_and_b32 s21, s22, 3
	v_cmp_le_i32_e32 vcc, s18, v212
	s_and_saveexec_b64 s[14:15], vcc
	s_cbranch_execnz .LBB0_489
.LBB0_485:
	s_or_b64 exec, exec, s[14:15]
	s_cmp_eq_u32 s99, 0
	s_cbranch_scc1 .Lfox1_nm3
	s_barrier
.Lfox1_nm3:
	s_andn2_b64 vcc, exec, s[12:13]
	s_cbranch_vccz .LBB0_494
	s_branch .LBB0_497
.LBB0_486:
	s_cmp_lg_u32 s99, 0
	s_cbranch_scc1 .Lfox1_noload
	v_add_u32_e32 v18, s18, v217
	v_mov_b64_e32 v[16:17], s[6:7]
	v_mad_i64_i32 v[16:17], s[4:5], v18, s65, v[16:17]
	v_lshl_add_u64 v[16:17], v[16:17], 0, s[2:3]
	v_lshl_add_u64 v[16:17], v[16:17], 0, v[160:161]
	v_add_co_u32_e32 v18, vcc, 0x1000, v16
	s_nop 1
	v_addc_co_u32_e32 v19, vcc, 0, v17, vcc
	v_add_co_u32_e32 v20, vcc, 0x2000, v16
	s_nop 1
	v_addc_co_u32_e32 v21, vcc, 0, v17, vcc
	s_mov_b32 s100, 0x68000
	s_mov_b32 s101, 0
	v_lshl_add_u64 v[100:101], v[18:19], 0, s[100:101]
	v_lshl_add_u64 v[102:103], v[20:21], 0, s[100:101]
	global_load_dwordx4 v[16:19], v[18:19], off offset:3072
	s_nop 0
	global_load_dwordx4 v[20:23], v[20:21], off
	global_load_dwordx4 v[196:199], v[100:101], off offset:3072
	global_load_dwordx2 v[170:171], v[102:103], off
	global_load_dword v162, v[102:103], off offset:8
	global_load_dword v168, v[102:103], off offset:12
	s_and_saveexec_b64 s[4:5], s[0:1]
	s_cbranch_execz .LBB0_488
	v_add_u32_e32 v24, s18, v216
	v_ashrrev_i32_e32 v25, 31, v24
	v_lshl_add_u64 v[24:25], v[24:25], 2, s[8:9]
	global_load_dword v208, v[24:25], off

; template <bool DIAG>
; DI void fox_tile(const bf16_t* sK, const bf16_t* sV, const float* sFk, const bf16x8 (&qf)[2][2], f32x4 (&o)[2][4], float (&mrun)[2], float (&lsum)[2], int key0, int qg0, int fr, int fq, int lane) {
;   const float SC2 = 0.125f * LOG2E;
;   f32x4 s[2][4];
;   const int kof = (fr * 64 + fq * 16) ^ ((fr >> 3) << 5);
; #pragma unroll
;   for (int t = 0; t < 4; ++t) {
;     const bf16x8 k0 = *(const bf16x8*)((const unsigned char*)sK + (t * 2) * 1024 + kof), k1 = *(const bf16x8*)((const unsigned char*)sK + (t * 2 + 1) * 1024 + kof);
; #pragma unroll
;     for (int mi = 0; mi < 2; ++mi) { s[mi][t] = mmaT(qf[mi][0], k0, (f32x4){0.f, 0.f, 0.f, 0.f}); s[mi][t] = mmaT(qf[mi][1], k1, s[mi][t]); }
;   }
;   f32x4 fk[4];
; #pragma unroll
;   for (int t = 0; t < 4; ++t) fk[t] = *(const f32x4*)(sFk + 16 * t + 4 * fq);
;   __builtin_amdgcn_sched_barrier(0);
;   bf16x8 vf[2][4];
; #pragma unroll
;   for (int k2 = 0; k2 < 2; ++k2)
; #pragma unroll
;     for (int d = 0; d < 4; ++d) {
;       const bf16_t* a = sV + (32 * k2 + 4 * fq + (fr >> 2)) * 72 + 16 * d + 4 * (fr & 3);
;       const v4i16_t lo = tr_rd(a), hi = tr_rd(a + 16 * 72);
;       vf[k2][d] = __builtin_shufflevector(lo, hi, 0, 1, 2, 3, 4, 5, 6, 7);
;     }
;   __builtin_amdgcn_sched_barrier(0);
; #pragma unroll
;   for (int mi = 0; mi < 2; ++mi) {
;     float mx = -INFINITY;
; #pragma unroll
;     for (int t = 0; t < 4; ++t)
; #pragma unroll
;       for (int j = 0; j < 4; ++j) {
;         float x = __builtin_fmaf(s[mi][t][j], SC2, fk[t][j]);
;         if (DIAG) { if (key0 + 16 * t + 4 * fq + j > qg0 + 16 * mi) x = -INFINITY; }
;         s[mi][t][j] = x; mx = fmaxf(mx, x);
; DI void fox_unit(const Params& p, int hf, int bl, int fh, int qb, unsigned char* shm, int tid, bool dry = false) {
;     ...
;     const int st = kt & 1;
;     if (kt + 1 < nkt) {
;       const size_t r = (size_t)((kt + 1) * 64 + skey) * NP;
;       kreg = *(const uint4*)(projb + r + C_FK + fh * 64 + sdg * 8); vreg = *(const uint4*)(projb + r + C_FV + fh * 64 + sdg * 8);
;       if (tid < 64) freg = (Fref - F[(kt + 1) * 64 + tid]) * LOG2E;
;     }
;     const bf16_t* sK = (const bf16_t*)(shm + st * STG); const bf16_t* sV = sK + 64 * 72; const float* sFk = (const float*)(sV + 64 * 72);
;     if (kt * 64 <= q0 + wid * 32 + 31) {
;       if (kt >= 4 * qb) fox_tile<true>(sK, sV, sFk, qf, o, mrun, lsum, kt * 64, qg0, fr, fq, lane);
.Lfox1_noload:
	s_and_b32 s21, s22, 3
	v_cmp_le_i32_e32 vcc, s18, v212
	s_and_saveexec_b64 s[14:15], vcc
	s_cbranch_execz .LBB0_485
.LBB0_489:
	s_mul_i32 s4, s21, 0x4900
	s_add_i32 s4, s4, 32
	v_add_u32_e32 v24, s4, v213
	ds_read_b128 v[64:67], v24
	ds_read_b128 v[68:71], v24 offset:1024
	ds_read_b128 v[56:59], v24 offset:2048
	ds_read_b128 v[60:63], v24 offset:3072
	ds_read_b128 v[48:51], v24 offset:4096
	ds_read_b128 v[52:55], v24 offset:5120
	ds_read_b128 v[40:43], v24 offset:6144
	ds_read_b128 v[44:47], v24 offset:7168
	v_lshl_add_u32 v24, v209, 2, s4
	ds_read_b128 v[36:39], v24 offset:18432
	ds_read_b128 v[32:35], v24 offset:18496
	ds_read_b128 v[28:31], v24 offset:18560
	ds_read_b128 v[24:27], v24 offset:18624
	v_lshl_add_u32 v72, v214, 1, s4
	s_cmp_lt_i32 s22, s17
	s_mov_b64 s[4:5], -1
	v_add_u32_e32 v221, v72, v215
	s_cbranch_scc1 .LBB0_491
	s_waitcnt lgkmcnt(11)
	v_mfma_f32_16x16x32_bf16 v[72:75], v[64:67], v[0:3], 0
	s_waitcnt lgkmcnt(10)
	v_mfma_f32_16x16x32_bf16 v[146:149], v[68:71], v[4:7], v[72:75]
	v_mfma_f32_16x16x32_bf16 v[72:75], v[64:67], v[8:11], 0
	v_mfma_f32_16x16x32_bf16 v[164:167], v[68:71], v[12:15], v[72:75]
	s_waitcnt lgkmcnt(9)
	v_mfma_f32_16x16x32_bf16 v[72:75], v[56:59], v[0:3], 0
	s_waitcnt lgkmcnt(8)
	v_mfma_f32_16x16x32_bf16 v[150:153], v[60:63], v[4:7], v[72:75]
	v_mfma_f32_16x16x32_bf16 v[72:75], v[56:59], v[8:11], 0
	v_mfma_f32_16x16x32_bf16 v[222:225], v[60:63], v[12:15], v[72:75]
	s_waitcnt lgkmcnt(7)
	v_mfma_f32_16x16x32_bf16 v[72:75], v[48:51], v[0:3], 0
	s_waitcnt lgkmcnt(6)
	v_mfma_f32_16x16x32_bf16 v[154:157], v[52:55], v[4:7], v[72:75]
	v_mfma_f32_16x16x32_bf16 v[72:75], v[48:51], v[8:11], 0
	v_mfma_f32_16x16x32_bf16 v[226:229], v[52:55], v[12:15], v[72:75]
	s_waitcnt lgkmcnt(5)
	v_mfma_f32_16x16x32_bf16 v[72:75], v[40:43], v[0:3], 0
	s_waitcnt lgkmcnt(4)
	v_mfma_f32_16x16x32_bf16 v[172:175], v[44:47], v[4:7], v[72:75]
	v_mfma_f32_16x16x32_bf16 v[72:75], v[40:43], v[8:11], 0
	v_mfma_f32_16x16x32_bf16 v[104:107], v[44:47], v[12:15], v[72:75]
	ds_read_b64_tr_b16 v[100:101], v221 offset:9216
	ds_read_b64_tr_b16 v[92:93], v221 offset:9248
	ds_read_b64_tr_b16 v[96:97], v221 offset:9280
	ds_read_b64_tr_b16 v[88:89], v221 offset:9312
	ds_read_b64_tr_b16 v[102:103], v221 offset:11520
	ds_read_b64_tr_b16 v[94:95], v221 offset:11552
	ds_read_b64_tr_b16 v[98:99], v221 offset:11584
	ds_read_b64_tr_b16 v[90:91], v221 offset:11616
	ds_read_b64_tr_b16 v[84:85], v221 offset:13824
	ds_read_b64_tr_b16 v[80:81], v221 offset:13856
	ds_read_b64_tr_b16 v[76:77], v221 offset:13888
	ds_read_b64_tr_b16 v[72:73], v221 offset:13920
	ds_read_b64_tr_b16 v[86:87], v221 offset:16128
	ds_read_b64_tr_b16 v[82:83], v221 offset:16160
	ds_read_b64_tr_b16 v[78:79], v221 offset:16192
	ds_read_b64_tr_b16 v[74:75], v221 offset:16224
	s_cmp_eq_u32 s99, 0
	s_cbranch_scc1 .Lfox1_nm1
	s_barrier
.Lfox1_nm1:
	v_add_u32_e32 v159, s18, v209
	s_waitcnt lgkmcnt(14)
	v_fmamk_f32 v147, v147, 0x3e38aa3b, v37
	v_cmp_lt_i32_e64 s[4:5], v159, v206
	v_add_u32_e32 v177, 2, v159
	v_fmamk_f32 v148, v148, 0x3e38aa3b, v38
	v_cndmask_b32_e64 v147, v200, v147, s[4:5]
	v_cmp_le_i32_e64 s[4:5], v177, v206
	v_add_u32_e32 v179, 3, v159
	v_fmamk_f32 v149, v149, 0x3e38aa3b, v39
	v_cndmask_b32_e64 v148, v200, v148, s[4:5]
	v_cmp_le_i32_e64 s[4:5], v179, v206
	v_add_u32_e32 v176, 16, v159
	v_fmamk_f32 v146, v146, 0x3e38aa3b, v36
	v_cmp_gt_i32_e32 vcc, v159, v206
	v_cndmask_b32_e64 v149, v200, v149, s[4:5]
	v_fmamk_f32 v150, v150, 0x3e38aa3b, v32
	v_cmp_le_i32_e64 s[4:5], v176, v206
	v_cndmask_b32_e32 v146, v146, v200, vcc
	s_mov_b32 s22, 0xff800000
	v_cndmask_b32_e64 v176, v200, v150, s[4:5]
	v_fmamk_f32 v150, v151, 0x3e38aa3b, v33
	v_add_u32_e32 v151, 17, v159
	v_max3_f32 v158, v146, s22, v147
	v_cmp_le_i32_e64 s[4:5], v151, v206
	v_add_u32_e32 v181, 18, v159
	v_max3_f32 v158, v158, v148, v149
	v_cndmask_b32_e64 v178, v200, v150, s[4:5]
	v_fmamk_f32 v152, v152, 0x3e38aa3b, v34
	v_cmp_le_i32_e64 s[4:5], v181, v206
	v_max3_f32 v150, v158, v176, v178
	v_add_u32_e32 v183, 32, v159
	v_cndmask_b32_e64 v158, v200, v152, s[4:5]
	v_fmamk_f32 v152, v153, 0x3e38aa3b, v35
	v_add_u32_e32 v153, 19, v159
	v_cmp_le_i32_e64 s[4:5], v153, v206
	v_add_u32_e32 v185, 34, v159
	v_add_u32_e32 v189, 48, v159
	v_cndmask_b32_e64 v180, v200, v152, s[4:5]
	v_fmamk_f32 v152, v154, 0x3e38aa3b, v28
	v_cmp_le_i32_e64 s[4:5], v183, v206
	v_add_u32_e32 v191, 50, v159
	v_max3_f32 v150, v150, v158, v180
	v_cndmask_b32_e64 v182, v200, v152, s[4:5]
	v_fmamk_f32 v152, v155, 0x3e38aa3b, v29
	v_add_u32_e32 v155, 33, v159
	v_cmp_le_i32_e64 s[4:5], v155, v206
	v_fmamk_f32 v104, v104, 0x3e38aa3b, v24
	s_nop 0
	v_cndmask_b32_e64 v184, v200, v152, s[4:5]
	v_fmamk_f32 v152, v156, 0x3e38aa3b, v30
	v_cmp_le_i32_e64 s[4:5], v185, v206
	v_max3_f32 v150, v150, v182, v184
	s_nop 0
	v_cndmask_b32_e64 v186, v200, v152, s[4:5]
	v_fmamk_f32 v152, v157, 0x3e38aa3b, v31
	v_add_u32_e32 v157, 35, v159
	v_cmp_le_i32_e64 s[4:5], v157, v206
	s_nop 1
	v_cndmask_b32_e64 v187, v200, v152, s[4:5]
	v_fmamk_f32 v152, v172, 0x3e38aa3b, v24
	v_cmp_le_i32_e64 s[4:5], v189, v206
	v_max3_f32 v150, v150, v186, v187
	s_nop 0
	v_cndmask_b32_e64 v188, v200, v152, s[4:5]
	v_fmamk_f32 v152, v173, 0x3e38aa3b, v25
	v_add_u32_e32 v173, 49, v159
	v_cmp_le_i32_e64 s[4:5], v173, v206
	s_nop 1
	v_cndmask_b32_e64 v190, v200, v152, s[4:5]
	v_fmamk_f32 v152, v174, 0x3e38aa3b, v26
	v_cmp_le_i32_e64 s[4:5], v191, v206
	v_max3_f32 v150, v150, v188, v190
	s_nop 0
	v_cndmask_b32_e64 v194, v200, v152, s[4:5]
	v_fmamk_f32 v152, v175, 0x3e38aa3b, v27
	v_add_u32_e32 v175, 51, v159
	v_cmp_le_i32_e64 s[4:5], v175, v206
	s_nop 1
	v_cndmask_b32_e64 v202, v200, v152, s[4:5]
	v_max3_f32 v150, v150, v194, v202
	ds_bpermute_b32 v152, v204, v150
	v_cmp_le_i32_e64 s[4:5], v159, v207
	s_waitcnt lgkmcnt(0)
; DI float ex2(float x) { return __builtin_amdgcn_exp2f(x); }
; DI float shx(float v, int m, int lane) { return __int_as_float(__builtin_amdgcn_ds_bpermute((lane ^ m) << 2, __float_as_int(v))); }
; template <bool DIAG>
; DI void fox_tile(const bf16_t* sK, const bf16_t* sV, const float* sFk, const bf16x8 (&qf)[2][2], f32x4 (&o)[2][4], float (&mrun)[2], float (&lsum)[2], int key0, int qg0, int fr, int fq, int lane) {
;     ...
;   for (int mi = 0; mi < 2; ++mi) {
;     float mx = -INFINITY;
; #pragma unroll
;     for (int t = 0; t < 4; ++t)
; #pragma unroll
;       for (int j = 0; j < 4; ++j) {
;         float x = __builtin_fmaf(s[mi][t][j], SC2, fk[t][j]);
;         if (DIAG) { if (key0 + 16 * t + 4 * fq + j > qg0 + 16 * mi) x = -INFINITY; }
;         s[mi][t][j] = x; mx = fmaxf(mx, x);
;       }
;     mx = fmaxf(mx, shx(mx, 16, lane)); mx = fmaxf(mx, shx(mx, 32, lane));
;     const float mnew = fmaxf(mrun[mi], mx), alpha = ex2(mrun[mi] - mnew);
;     mrun[mi] = mnew;
;     float ps = 0.f;
; #pragma unroll
;     for (int t = 0; t < 4; ++t)
; #pragma unroll
;       for (int j = 0; j < 4; ++j) { const float pv = ex2(s[mi][t][j] - mnew); s[mi][t][j] = pv; ps += pv; }
;     lsum[mi] = lsum[mi] * alpha + ps;
; #pragma unroll
;     for (int d = 0; d < 4; ++d) o[mi][d] *= alpha;
;   }
	v_max_f32_e32 v152, v152, v152
	v_max_f32_e32 v150, v150, v152
	ds_bpermute_b32 v152, v169, v150
	s_waitcnt lgkmcnt(0)
	v_max3_f32 v220, v219, v150, v152
	v_sub_f32_e32 v147, v147, v220
	v_exp_f32_e32 v150, v147
	v_sub_f32_e32 v147, v148, v220
	v_exp_f32_e32 v148, v147
	v_sub_f32_e32 v147, v149, v220
	v_exp_f32_e32 v152, v147
	v_sub_f32_e32 v147, v176, v220
	v_exp_f32_e32 v156, v147
	v_sub_f32_e32 v147, v178, v220
	v_exp_f32_e32 v154, v147
	v_sub_f32_e32 v147, v158, v220
	v_exp_f32_e32 v158, v147
	v_sub_f32_e32 v147, v180, v220
	v_exp_f32_e32 v174, v147
	v_sub_f32_e32 v147, v182, v220
	v_exp_f32_e32 v172, v147
	v_sub_f32_e32 v147, v184, v220
	v_exp_f32_e32 v176, v147
	v_sub_f32_e32 v147, v186, v220
	v_exp_f32_e32 v180, v147
	v_sub_f32_e32 v147, v187, v220
	v_exp_f32_e32 v178, v147
	v_sub_f32_e32 v147, v188, v220
	v_exp_f32_e32 v182, v147
	v_sub_f32_e32 v147, v190, v220
	v_exp_f32_e32 v186, v147
	v_sub_f32_e32 v147, v194, v220
	v_exp_f32_e32 v184, v147
	v_sub_f32_e32 v147, v202, v220
	v_exp_f32_e32 v190, v147
	v_fmamk_f32 v147, v164, 0x3e38aa3b, v36
	v_cndmask_b32_e64 v147, v200, v147, s[4:5]
	v_fmamk_f32 v149, v165, 0x3e38aa3b, v37
	v_cmp_lt_i32_e64 s[4:5], v159, v207
	v_fmamk_f32 v164, v166, 0x3e38aa3b, v38
	v_sub_f32_e32 v230, v219, v220
	v_cndmask_b32_e64 v149, v200, v149, s[4:5]
	v_cmp_le_i32_e64 s[4:5], v177, v207
	v_max3_f32 v159, v147, s22, v149
	v_exp_f32_e32 v188, v230
	v_cndmask_b32_e64 v177, v200, v164, s[4:5]
	v_fmamk_f32 v164, v167, 0x3e38aa3b, v39
	v_cmp_le_i32_e64 s[4:5], v179, v207
	v_pk_mul_f32 v[166:167], v[140:141], v[188:189] op_sel_hi:[1,0]
	v_pk_mul_f32 v[230:231], v[132:133], v[188:189] op_sel_hi:[1,0]
	v_cndmask_b32_e64 v179, v200, v164, s[4:5]
	v_fmamk_f32 v164, v222, 0x3e38aa3b, v32
	v_cndmask_b32_e32 v187, v164, v200, vcc
	v_fmamk_f32 v164, v223, 0x3e38aa3b, v33
	v_cmp_le_i32_e32 vcc, v151, v207
	v_max3_f32 v159, v159, v177, v179
	v_sub_f32_e32 v146, v146, v220
	v_cndmask_b32_e32 v194, v200, v164, vcc
	v_max3_f32 v151, v159, v187, v194
	v_fmamk_f32 v159, v224, 0x3e38aa3b, v34
	v_cmp_le_i32_e32 vcc, v181, v207
	v_fmamk_f32 v164, v225, 0x3e38aa3b, v35
	v_pk_mul_f32 v[224:225], v[134:135], v[188:189] op_sel_hi:[1,0]
	v_cndmask_b32_e32 v159, v200, v159, vcc
	v_cmp_le_i32_e32 vcc, v153, v207
	v_fmamk_f32 v153, v226, 0x3e38aa3b, v28
	v_exp_f32_e32 v146, v146
	v_cndmask_b32_e32 v181, v200, v164, vcc
	v_cmp_le_i32_e32 vcc, v183, v207
	v_max3_f32 v151, v151, v159, v181
	v_pk_mul_f32 v[164:165], v[138:139], v[188:189] op_sel_hi:[1,0]
	v_cndmask_b32_e32 v183, v200, v153, vcc
	v_fmamk_f32 v153, v227, 0x3e38aa3b, v29
	v_cmp_le_i32_e32 vcc, v155, v207
	v_pk_mul_f32 v[226:227], v[136:137], v[188:189] op_sel_hi:[1,0]
	v_cvt_pk_bf16_f32 v236, v146, v150
	v_cvt_pk_bf16_f32 v237, v148, v152
	v_cvt_pk_bf16_f32 v238, v156, v154
	v_cvt_pk_bf16_f32 v239, v158, v174
	s_nop 0
	v_cndmask_b32_e32 v202, v200, v153, vcc
	v_fmamk_f32 v153, v228, 0x3e38aa3b, v30
	v_cmp_le_i32_e32 vcc, v185, v207
	v_max3_f32 v151, v151, v183, v202
	v_mfma_f32_16x16x32_bf16 v[164:167], v[92:95], v[236:239], v[164:167]
	v_cndmask_b32_e32 v185, v200, v153, vcc
	v_fmamk_f32 v153, v229, 0x3e38aa3b, v31
	v_cmp_le_i32_e32 vcc, v157, v207
	v_pk_mul_f32 v[228:229], v[130:131], v[188:189] op_sel_hi:[1,0]
	v_mfma_f32_16x16x32_bf16 v[224:227], v[96:99], v[236:239], v[224:227]
	v_cndmask_b32_e32 v223, v200, v153, vcc
	v_cmp_le_i32_e32 vcc, v189, v207
	v_max3_f32 v151, v151, v185, v223
	v_mfma_f32_16x16x32_bf16 v[228:231], v[88:91], v[236:239], v[228:231]
	v_cndmask_b32_e32 v244, v200, v104, vcc
	v_fmamk_f32 v104, v105, 0x3e38aa3b, v25
	v_cmp_le_i32_e32 vcc, v173, v207
	v_fmamk_f32 v105, v106, 0x3e38aa3b, v26
	s_mov_b64 s[4:5], 0
	v_cndmask_b32_e32 v245, v200, v104, vcc
	v_cmp_le_i32_e32 vcc, v191, v207
	v_max3_f32 v104, v151, v244, v245
	s_nop 0
	v_cndmask_b32_e32 v191, v200, v105, vcc
	v_fmamk_f32 v105, v107, 0x3e38aa3b, v27
	v_cmp_le_i32_e32 vcc, v175, v207
	v_pk_mul_f32 v[106:107], v[144:145], v[188:189] op_sel_hi:[1,0]
	s_nop 0
	v_cndmask_b32_e32 v249, v200, v105, vcc
	v_max3_f32 v151, v104, v191, v249
	ds_bpermute_b32 v153, v204, v151
	v_pk_mul_f32 v[104:105], v[142:143], v[188:189] op_sel_hi:[1,0]
	s_waitcnt lgkmcnt(0)
	v_max_f32_e32 v153, v153, v153
	v_max_f32_e32 v151, v151, v153
	ds_bpermute_b32 v153, v169, v151
	v_mfma_f32_16x16x32_bf16 v[104:107], v[100:103], v[236:239], v[104:107]
	s_waitcnt lgkmcnt(0)
; DI float ex2(float x) { return __builtin_amdgcn_exp2f(x); }
; template <bool DIAG>
; DI void fox_tile(const bf16_t* sK, const bf16_t* sV, const float* sFk, const bf16x8 (&qf)[2][2], f32x4 (&o)[2][4], float (&mrun)[2], float (&lsum)[2], int key0, int qg0, int fr, int fq, int lane) {
;   const float SC2 = 0.125f * LOG2E;
;   f32x4 s[2][4];
;   const int kof = (fr * 64 + fq * 16) ^ ((fr >> 3) << 5);
; #pragma unroll
;   for (int t = 0; t < 4; ++t) {
;     const bf16x8 k0 = *(const bf16x8*)((const unsigned char*)sK + (t * 2) * 1024 + kof), k1 = *(const bf16x8*)((const unsigned char*)sK + (t * 2 + 1) * 1024 + kof);
; #pragma unroll
;     for (int mi = 0; mi < 2; ++mi) { s[mi][t] = mmaT(qf[mi][0], k0, (f32x4){0.f, 0.f, 0.f, 0.f}); s[mi][t] = mmaT(qf[mi][1], k1, s[mi][t]); }
;   }
;   f32x4 fk[4];
; #pragma unroll
;   for (int t = 0; t < 4; ++t) fk[t] = *(const f32x4*)(sFk + 16 * t + 4 * fq);
;   __builtin_amdgcn_sched_barrier(0);
;   bf16x8 vf[2][4];
; #pragma unroll
;   for (int k2 = 0; k2 < 2; ++k2)
; #pragma unroll
;     for (int d = 0; d < 4; ++d) {
;       const bf16_t* a = sV + (32 * k2 + 4 * fq + (fr >> 2)) * 72 + 16 * d + 4 * (fr & 3);
;       const v4i16_t lo = tr_rd(a), hi = tr_rd(a + 16 * 72);
;       vf[k2][d] = __builtin_shufflevector(lo, hi, 0, 1, 2, 3, 4, 5, 6, 7);
;     }
;   __builtin_amdgcn_sched_barrier(0);
; #pragma unroll
;   for (int mi = 0; mi < 2; ++mi) {
;     float mx = -INFINITY;
; #pragma unroll
;     for (int t = 0; t < 4; ++t)
; #pragma unroll
;       for (int j = 0; j < 4; ++j) {
;         float x = __builtin_fmaf(s[mi][t][j], SC2, fk[t][j]);
;         if (DIAG) { if (key0 + 16 * t + 4 * fq + j > qg0 + 16 * mi) x = -INFINITY; }
;         s[mi][t][j] = x; mx = fmaxf(mx, x);
;       }
;     mx = fmaxf(mx, shx(mx, 16, lane)); mx = fmaxf(mx, shx(mx, 32, lane));
;     const float mnew = fmaxf(mrun[mi], mx), alpha = ex2(mrun[mi] - mnew);
;     mrun[mi] = mnew;
;     float ps = 0.f;
; #pragma unroll
;     for (int t = 0; t < 4; ++t)
; #pragma unroll
;       for (int j = 0; j < 4; ++j) { const float pv = ex2(s[mi][t][j] - mnew); s[mi][t][j] = pv; ps += pv; }
;     lsum[mi] = lsum[mi] * alpha + ps;
; #pragma unroll
;     for (int d = 0; d < 4; ++d) o[mi][d] *= alpha;
;   }
; #pragma unroll
;   for (int k2 = 0; k2 < 2; ++k2) {
;     bf16x8 pa[2];
; #pragma unroll
	v_max3_f32 v222, v218, v151, v153
	v_sub_f32_e32 v173, v218, v222
	v_exp_f32_e32 v189, v173
	v_sub_f32_e32 v149, v149, v222
	v_sub_f32_e32 v155, v187, v222
	v_sub_f32_e32 v147, v147, v222
	v_mov_b32_e32 v248, v189
	v_exp_f32_e32 v151, v149
	v_sub_f32_e32 v149, v177, v222
	v_sub_f32_e32 v153, v179, v222
	v_exp_f32_e32 v157, v155
	v_sub_f32_e32 v155, v194, v222
	v_sub_f32_e32 v159, v159, v222
	v_sub_f32_e32 v175, v181, v222
	v_pk_mul_f32 v[234:235], v[124:125], v[248:249] op_sel_hi:[1,0]
	v_pk_mul_f32 v[232:233], v[122:123], v[248:249] op_sel_hi:[1,0]
	v_exp_f32_e32 v147, v147
	v_exp_f32_e32 v149, v149
	v_exp_f32_e32 v153, v153
	v_exp_f32_e32 v155, v155
	v_exp_f32_e32 v159, v159
	v_exp_f32_e32 v175, v175
	v_cvt_pk_bf16_f32 v240, v147, v151
	v_cvt_pk_bf16_f32 v241, v149, v153
	v_cvt_pk_bf16_f32 v242, v157, v155
	v_cvt_pk_bf16_f32 v243, v159, v175
	v_sub_f32_e32 v177, v183, v222
	v_mfma_f32_16x16x32_bf16 v[100:103], v[100:103], v[240:243], v[232:235]
	v_sub_f32_e32 v179, v185, v222
	v_exp_f32_e32 v173, v177
	v_sub_f32_e32 v177, v202, v222
	v_pk_mul_f32 v[234:235], v[120:121], v[248:249] op_sel_hi:[1,0]
	v_pk_mul_f32 v[232:233], v[118:119], v[248:249] op_sel_hi:[1,0]
	v_exp_f32_e32 v181, v179
	v_sub_f32_e32 v179, v223, v222
	v_mfma_f32_16x16x32_bf16 v[232:235], v[92:95], v[240:243], v[232:235]
	v_sub_f32_e32 v92, v244, v222
	v_exp_f32_e32 v183, v92
	v_sub_f32_e32 v92, v245, v222
	v_exp_f32_e32 v187, v92
	v_pk_mul_f32 v[94:95], v[116:117], v[248:249] op_sel_hi:[1,0]
	v_pk_mul_f32 v[92:93], v[114:115], v[248:249] op_sel_hi:[1,0]
	v_exp_f32_e32 v177, v177
	v_exp_f32_e32 v179, v179
	v_mfma_f32_16x16x32_bf16 v[244:247], v[96:99], v[240:243], v[92:95]
	s_nop 2
	v_sub_f32_e32 v92, v191, v222
	v_exp_f32_e32 v185, v92
	v_sub_f32_e32 v92, v249, v222
	v_exp_f32_e32 v191, v92
	v_pk_mul_f32 v[94:95], v[112:113], v[248:249] op_sel_hi:[1,0]
	v_pk_mul_f32 v[92:93], v[110:111], v[248:249] op_sel_hi:[1,0]
	s_nop 1
	v_mfma_f32_16x16x32_bf16 v[236:239], v[88:91], v[240:243], v[92:95]
	v_cvt_pk_bf16_f32 v240, v172, v176
	v_cvt_pk_bf16_f32 v241, v180, v178
	v_cvt_pk_bf16_f32 v242, v182, v186
	v_cvt_pk_bf16_f32 v243, v184, v190
	v_cvt_pk_bf16_f32 v248, v173, v177
	v_cvt_pk_bf16_f32 v249, v181, v179
	v_cvt_pk_bf16_f32 v250, v183, v187
	v_cvt_pk_bf16_f32 v251, v185, v191
	s_nop 0
	v_mfma_f32_16x16x32_bf16 v[88:91], v[84:87], v[240:243], v[104:107]
	v_mfma_f32_16x16x32_bf16 v[92:95], v[84:87], v[248:251], v[100:103]
	v_add_f32_e64 v84, v146, 0
	v_add_f32_e64 v85, v147, 0
	v_pk_add_f32 v[96:97], v[150:151], v[84:85]
	v_mfma_f32_16x16x32_bf16 v[84:87], v[80:83], v[240:243], v[164:167]
	v_add_f32_e64 v96, v148, v96
	v_add_f32_e64 v97, v149, v97
	v_pk_add_f32 v[96:97], v[152:153], v[96:97]
	s_nop 0
	v_pk_add_f32 v[100:101], v[156:157], v[96:97]
	v_mfma_f32_16x16x32_bf16 v[96:99], v[80:83], v[248:251], v[232:235]
	v_add_f32_e64 v80, v154, v100
	v_add_f32_e64 v81, v155, v101
	v_pk_add_f32 v[80:81], v[158:159], v[80:81]
	s_nop 0
	v_pk_add_f32 v[100:101], v[174:175], v[80:81]
	v_mfma_f32_16x16x32_bf16 v[80:83], v[76:79], v[240:243], v[224:227]
	v_add_f32_e64 v100, v172, v100
	v_add_f32_e64 v101, v173, v101
	v_pk_add_f32 v[100:101], v[176:177], v[100:101]
	s_nop 0
	v_pk_add_f32 v[104:105], v[180:181], v[100:101]
	v_mfma_f32_16x16x32_bf16 v[100:103], v[76:79], v[248:251], v[244:247]
	v_add_f32_e64 v76, v178, v104
	v_add_f32_e64 v77, v179, v105
	v_pk_add_f32 v[76:77], v[182:183], v[76:77]
	s_nop 0
	v_pk_add_f32 v[104:105], v[186:187], v[76:77]
	v_mfma_f32_16x16x32_bf16 v[76:79], v[72:75], v[240:243], v[228:231]
	v_add_f32_e64 v104, v184, v104
	v_add_f32_e64 v105, v185, v105
	v_pk_add_f32 v[104:105], v[190:191], v[104:105]
	v_mfma_f32_16x16x32_bf16 v[72:75], v[72:75], v[248:251], v[236:239]
	v_fma_f32 v104, v128, v188, v104
	v_fma_f32 v105, v129, v189, v105
.LBB0_491:
	s_andn2_b64 vcc, exec, s[4:5]
	s_cbranch_vccnz .LBB0_493
	s_waitcnt lgkmcnt(11)
	v_mfma_f32_16x16x32_bf16 v[72:75], v[64:67], v[0:3], v[224:227]
	v_mfma_f32_16x16x32_bf16 v[84:87], v[64:67], v[8:11], v[228:231]
	s_waitcnt lgkmcnt(10)
	v_mfma_f32_16x16x32_bf16 v[72:75], v[68:71], v[4:7], v[72:75]
	v_mfma_f32_16x16x32_bf16 v[84:87], v[68:71], v[12:15], v[84:87]
	s_waitcnt lgkmcnt(9)
	v_mfma_f32_16x16x32_bf16 v[76:79], v[56:59], v[0:3], v[224:227]
	v_mfma_f32_16x16x32_bf16 v[88:91], v[56:59], v[8:11], v[228:231]
	s_waitcnt lgkmcnt(8)
	v_mfma_f32_16x16x32_bf16 v[76:79], v[60:63], v[4:7], v[76:79]
	v_mfma_f32_16x16x32_bf16 v[88:91], v[60:63], v[12:15], v[88:91]
	s_waitcnt lgkmcnt(7)
	v_mfma_f32_16x16x32_bf16 v[80:83], v[48:51], v[0:3], v[224:227]
	v_mfma_f32_16x16x32_bf16 v[92:95], v[48:51], v[8:11], v[228:231]
	s_waitcnt lgkmcnt(6)
	v_mfma_f32_16x16x32_bf16 v[80:83], v[52:55], v[4:7], v[80:83]
	v_mfma_f32_16x16x32_bf16 v[92:95], v[52:55], v[12:15], v[92:95]
	s_waitcnt lgkmcnt(5)
	v_mfma_f32_16x16x32_bf16 v[96:99], v[40:43], v[0:3], v[224:227]
	v_mfma_f32_16x16x32_bf16 v[164:167], v[40:43], v[8:11], v[228:231]
	s_waitcnt lgkmcnt(4)
	v_mfma_f32_16x16x32_bf16 v[96:99], v[44:47], v[4:7], v[96:99]
	v_mfma_f32_16x16x32_bf16 v[164:167], v[44:47], v[12:15], v[164:167]
	s_waitcnt lgkmcnt(0)
	v_fmamk_f32 v72, v72, 0x3e38aa3b, v36
	v_fmamk_f32 v73, v73, 0x3e38aa3b, v37
	v_fmamk_f32 v74, v74, 0x3e38aa3b, v38
	v_fmamk_f32 v75, v75, 0x3e38aa3b, v39
	v_fmamk_f32 v84, v84, 0x3e38aa3b, v36
	v_fmamk_f32 v85, v85, 0x3e38aa3b, v37
	v_fmamk_f32 v86, v86, 0x3e38aa3b, v38
	v_fmamk_f32 v87, v87, 0x3e38aa3b, v39
	v_fmamk_f32 v76, v76, 0x3e38aa3b, v32
	v_fmamk_f32 v77, v77, 0x3e38aa3b, v33
	v_fmamk_f32 v78, v78, 0x3e38aa3b, v34
	v_fmamk_f32 v79, v79, 0x3e38aa3b, v35
	v_fmamk_f32 v88, v88, 0x3e38aa3b, v32
	v_fmamk_f32 v89, v89, 0x3e38aa3b, v33
	v_fmamk_f32 v90, v90, 0x3e38aa3b, v34
	v_fmamk_f32 v91, v91, 0x3e38aa3b, v35
	v_fmamk_f32 v80, v80, 0x3e38aa3b, v28
	v_fmamk_f32 v81, v81, 0x3e38aa3b, v29
	v_fmamk_f32 v82, v82, 0x3e38aa3b, v30
	v_fmamk_f32 v83, v83, 0x3e38aa3b, v31
	v_fmamk_f32 v92, v92, 0x3e38aa3b, v28
	v_fmamk_f32 v93, v93, 0x3e38aa3b, v29
	v_fmamk_f32 v94, v94, 0x3e38aa3b, v30
	v_fmamk_f32 v95, v95, 0x3e38aa3b, v31
	v_fmamk_f32 v96, v96, 0x3e38aa3b, v24
	v_fmamk_f32 v97, v97, 0x3e38aa3b, v25
	v_fmamk_f32 v98, v98, 0x3e38aa3b, v26
	v_fmamk_f32 v99, v99, 0x3e38aa3b, v27
	v_fmamk_f32 v164, v164, 0x3e38aa3b, v24
	v_fmamk_f32 v165, v165, 0x3e38aa3b, v25
	v_fmamk_f32 v166, v166, 0x3e38aa3b, v26
	v_fmamk_f32 v167, v167, 0x3e38aa3b, v27
	v_max3_f32 v146, v72, v73, v74
	v_max3_f32 v147, v80, v81, v82
	v_max3_f32 v146, v146, v75, v84
	v_max3_f32 v147, v147, v83, v92
	v_max3_f32 v146, v146, v85, v86
	v_max3_f32 v147, v147, v93, v94
	v_max3_f32 v146, v146, v87, v76
	v_max3_f32 v147, v147, v95, v96
	v_max3_f32 v146, v146, v77, v78
	v_max3_f32 v147, v147, v97, v98
	v_max3_f32 v146, v146, v79, v88
	v_max3_f32 v147, v147, v99, v164
	v_max3_f32 v146, v146, v89, v90
	v_max3_f32 v147, v147, v165, v166
	v_max3_f32 v146, v146, v91, v91
	v_max3_f32 v147, v147, v167, v167
	v_max_f32_e32 v146, v146, v147
	v_cmp_lt_f32_e32 vcc, 0x42a00000, v146
	s_cbranch_vccnz .Lfox1_slow
; DI unsigned pk2(float lo, float hi) { unsigned r; asm volatile("v_cvt_pk_bf16_f32 %0, %1, %2" : "=v"(r) : "v"(lo), "v"(hi)); return r; }
; DI float ex2(float x) { return __builtin_amdgcn_exp2f(x); }
; DI f32x4 mmaT(bf16x8 a_m, bf16x8 b_n, f32x4 c) { return __builtin_amdgcn_mfma_f32_16x16x32_bf16(b_n, a_m, c, 0, 0, 0); }
; template <bool DIAG>
; DI void fox_tile(const bf16_t* sK, const bf16_t* sV, const float* sFk, const bf16x8 (&qf)[2][2], f32x4 (&o)[2][4], float (&mrun)[2], float (&lsum)[2], int key0, int qg0, int fr, int fq, int lane) {
;     ...
;   bf16x8 vf[2][4];
; #pragma unroll
;   for (int k2 = 0; k2 < 2; ++k2)
; #pragma unroll
;     for (int d = 0; d < 4; ++d) {
;       const bf16_t* a = sV + (32 * k2 + 4 * fq + (fr >> 2)) * 72 + 16 * d + 4 * (fr & 3);
;       const v4i16_t lo = tr_rd(a), hi = tr_rd(a + 16 * 72);
;       vf[k2][d] = __builtin_shufflevector(lo, hi, 0, 1, 2, 3, 4, 5, 6, 7);
;     }
;   __builtin_amdgcn_sched_barrier(0);
; #pragma unroll
;   for (int mi = 0; mi < 2; ++mi) {
;     float mx = -INFINITY;
; #pragma unroll
;     for (int t = 0; t < 4; ++t)
; #pragma unroll
;       for (int j = 0; j < 4; ++j) {
;         float x = __builtin_fmaf(s[mi][t][j], SC2, fk[t][j]);
;         if (DIAG) { if (key0 + 16 * t + 4 * fq + j > qg0 + 16 * mi) x = -INFINITY; }
;         s[mi][t][j] = x; mx = fmaxf(mx, x);
;       }
;     mx = fmaxf(mx, shx(mx, 16, lane)); mx = fmaxf(mx, shx(mx, 32, lane));
;     const float mnew = fmaxf(mrun[mi], mx), alpha = ex2(mrun[mi] - mnew);
;     mrun[mi] = mnew;
;     float ps = 0.f;
; #pragma unroll
;     for (int t = 0; t < 4; ++t)
; #pragma unroll
;       for (int j = 0; j < 4; ++j) { const float pv = ex2(s[mi][t][j] - mnew); s[mi][t][j] = pv; ps += pv; }
;     lsum[mi] = lsum[mi] * alpha + ps;
; #pragma unroll
;     for (int d = 0; d < 4; ++d) o[mi][d] *= alpha;
;   }
; #pragma unroll
;   for (int k2 = 0; k2 < 2; ++k2) {
;     bf16x8 pa[2];
; #pragma unroll
;     for (int mi = 0; mi < 2; ++mi) pa[mi] = mk8(pk2(s[mi][2 * k2][0], s[mi][2 * k2][1]), pk2(s[mi][2 * k2][2], s[mi][2 * k2][3]), pk2(s[mi][2 * k2 + 1][0], s[mi][2 * k2 + 1][1]), pk2(s[mi][2 * k2 + 1][2], s[mi][2 * k2 + 1][3]));
; #pragma unroll
;     for (int d = 0; d < 4; ++d) {
; #pragma unroll
;       for (int mi = 0; mi < 2; ++mi) o[mi][d] = mmaT(pa[mi], vf[k2][d], o[mi][d]);
;     }
	ds_read_b64_tr_b16 v[68:69], v221 offset:9216
	ds_read_b64_tr_b16 v[60:61], v221 offset:9248
	ds_read_b64_tr_b16 v[64:65], v221 offset:9280
	ds_read_b64_tr_b16 v[56:57], v221 offset:9312
	ds_read_b64_tr_b16 v[70:71], v221 offset:11520
	ds_read_b64_tr_b16 v[62:63], v221 offset:11552
	ds_read_b64_tr_b16 v[66:67], v221 offset:11584
	ds_read_b64_tr_b16 v[58:59], v221 offset:11616
	ds_read_b64_tr_b16 v[52:53], v221 offset:13824
	ds_read_b64_tr_b16 v[48:49], v221 offset:13856
	ds_read_b64_tr_b16 v[44:45], v221 offset:13888
	ds_read_b64_tr_b16 v[40:41], v221 offset:13920
	ds_read_b64_tr_b16 v[54:55], v221 offset:16128
	ds_read_b64_tr_b16 v[50:51], v221 offset:16160
	ds_read_b64_tr_b16 v[46:47], v221 offset:16192
	ds_read_b64_tr_b16 v[42:43], v221 offset:16224
	v_exp_f32_e32 v72, v72
	v_exp_f32_e32 v73, v73
	v_exp_f32_e32 v74, v74
	v_exp_f32_e32 v75, v75
	v_exp_f32_e32 v76, v76
	v_exp_f32_e32 v77, v77
	v_exp_f32_e32 v78, v78
	v_exp_f32_e32 v79, v79
	v_exp_f32_e32 v80, v80
	v_exp_f32_e32 v81, v81
	v_exp_f32_e32 v82, v82
	v_exp_f32_e32 v83, v83
	v_exp_f32_e32 v96, v96
	v_exp_f32_e32 v97, v97
	v_exp_f32_e32 v98, v98
	v_exp_f32_e32 v99, v99
	v_add_f32_e32 v146, v72, v73
	v_add_f32_e32 v147, v74, v75
	v_add_f32_e32 v148, v76, v77
	v_add_f32_e32 v149, v78, v79
	v_add_f32_e32 v150, v80, v81
	v_add_f32_e32 v151, v82, v83
	v_add_f32_e32 v152, v96, v97
	v_add_f32_e32 v153, v98, v99
	v_add_f32_e32 v146, v146, v147
	v_add_f32_e32 v147, v148, v149
	v_add_f32_e32 v148, v150, v151
	v_add_f32_e32 v149, v152, v153
	v_add_f32_e32 v146, v146, v147
	v_add_f32_e32 v148, v148, v149
	v_add_f32_e32 v146, v146, v148
	v_add_f32_e32 v128, v128, v146
	v_cvt_pk_bf16_f32 v36, v72, v73
	v_cvt_pk_bf16_f32 v37, v74, v75
	v_cvt_pk_bf16_f32 v38, v76, v77
	v_cvt_pk_bf16_f32 v39, v78, v79
	v_cvt_pk_bf16_f32 v28, v80, v81
	v_cvt_pk_bf16_f32 v29, v82, v83
	v_cvt_pk_bf16_f32 v30, v96, v97
	v_cvt_pk_bf16_f32 v31, v98, v99
	s_cmp_eq_u32 s99, 0
	s_cbranch_scc1 .Lfox1_nm2
	s_barrier
.Lfox1_nm2:
	s_waitcnt lgkmcnt(8)
	v_mfma_f32_16x16x32_bf16 v[142:145], v[68:71], v[36:39], v[142:145]
	v_exp_f32_e32 v84, v84
	v_exp_f32_e32 v85, v85
	v_mfma_f32_16x16x32_bf16 v[138:141], v[60:63], v[36:39], v[138:141]
	v_exp_f32_e32 v86, v86
	v_exp_f32_e32 v87, v87
	v_mfma_f32_16x16x32_bf16 v[134:137], v[64:67], v[36:39], v[134:137]
	v_exp_f32_e32 v88, v88
	v_exp_f32_e32 v89, v89
	v_mfma_f32_16x16x32_bf16 v[130:133], v[56:59], v[36:39], v[130:133]
	v_exp_f32_e32 v90, v90
	v_exp_f32_e32 v91, v91
	s_waitcnt lgkmcnt(0)
	v_mfma_f32_16x16x32_bf16 v[142:145], v[52:55], v[28:31], v[142:145]
	v_exp_f32_e32 v92, v92
	v_exp_f32_e32 v93, v93
	v_mfma_f32_16x16x32_bf16 v[138:141], v[48:51], v[28:31], v[138:141]
	v_exp_f32_e32 v94, v94
	v_exp_f32_e32 v95, v95
	v_mfma_f32_16x16x32_bf16 v[134:137], v[44:47], v[28:31], v[134:137]
	v_exp_f32_e32 v164, v164
	v_exp_f32_e32 v165, v165
	v_mfma_f32_16x16x32_bf16 v[130:133], v[40:43], v[28:31], v[130:133]
	v_exp_f32_e32 v166, v166
	v_exp_f32_e32 v167, v167
	v_add_f32_e32 v146, v84, v85
	v_add_f32_e32 v147, v86, v87
	v_add_f32_e32 v148, v88, v89
	v_add_f32_e32 v149, v90, v91
	v_add_f32_e32 v150, v92, v93
	v_add_f32_e32 v151, v94, v95
	v_add_f32_e32 v152, v164, v165
	v_add_f32_e32 v153, v166, v167
	v_add_f32_e32 v146, v146, v147
	v_add_f32_e32 v147, v148, v149
	v_add_f32_e32 v148, v150, v151
	v_add_f32_e32 v149, v152, v153
	v_add_f32_e32 v146, v146, v147
	v_add_f32_e32 v148, v148, v149
	v_add_f32_e32 v146, v146, v148
	v_add_f32_e32 v129, v129, v146
	v_cvt_pk_bf16_f32 v32, v84, v85
	v_cvt_pk_bf16_f32 v33, v86, v87
	v_cvt_pk_bf16_f32 v34, v88, v89
	v_cvt_pk_bf16_f32 v35, v90, v91
	v_cvt_pk_bf16_f32 v24, v92, v93
	v_cvt_pk_bf16_f32 v25, v94, v95
	v_cvt_pk_bf16_f32 v26, v164, v165
	v_cvt_pk_bf16_f32 v27, v166, v167
	s_nop 1
	v_mfma_f32_16x16x32_bf16 v[122:125], v[68:71], v[32:35], v[122:125]
	v_mfma_f32_16x16x32_bf16 v[118:121], v[60:63], v[32:35], v[118:121]
	v_mfma_f32_16x16x32_bf16 v[114:117], v[64:67], v[32:35], v[114:117]
	v_mfma_f32_16x16x32_bf16 v[110:113], v[56:59], v[32:35], v[110:113]
	v_mfma_f32_16x16x32_bf16 v[122:125], v[52:55], v[24:27], v[122:125]
	v_mfma_f32_16x16x32_bf16 v[118:121], v[48:51], v[24:27], v[118:121]
	v_mfma_f32_16x16x32_bf16 v[114:117], v[44:47], v[24:27], v[114:117]
	v_mfma_f32_16x16x32_bf16 v[110:113], v[40:43], v[24:27], v[110:113]
	s_branch .Lfox1_join
.Lfox1_slow:
	s_waitcnt lgkmcnt(11)
	v_mfma_f32_16x16x32_bf16 v[72:75], v[64:67], v[0:3], 0
	v_mfma_f32_16x16x32_bf16 v[64:67], v[64:67], v[8:11], 0
	s_waitcnt lgkmcnt(10)
	v_mfma_f32_16x16x32_bf16 v[84:87], v[68:71], v[12:15], v[64:67]
	s_waitcnt lgkmcnt(9)
	v_mfma_f32_16x16x32_bf16 v[64:67], v[56:59], v[0:3], 0
	v_mfma_f32_16x16x32_bf16 v[56:59], v[56:59], v[8:11], 0
	s_waitcnt lgkmcnt(8)
	v_mfma_f32_16x16x32_bf16 v[88:91], v[60:63], v[12:15], v[56:59]
	s_waitcnt lgkmcnt(7)
	v_mfma_f32_16x16x32_bf16 v[56:59], v[48:51], v[0:3], 0
	v_mfma_f32_16x16x32_bf16 v[48:51], v[48:51], v[8:11], 0
	s_waitcnt lgkmcnt(6)
	v_mfma_f32_16x16x32_bf16 v[92:95], v[52:55], v[12:15], v[48:51]
	s_waitcnt lgkmcnt(5)
	v_mfma_f32_16x16x32_bf16 v[48:51], v[40:43], v[0:3], 0
	v_mfma_f32_16x16x32_bf16 v[72:75], v[68:71], v[4:7], v[72:75]
	v_mfma_f32_16x16x32_bf16 v[76:79], v[60:63], v[4:7], v[64:67]
	v_mfma_f32_16x16x32_bf16 v[80:83], v[52:55], v[4:7], v[56:59]
	s_waitcnt lgkmcnt(4)
	v_mfma_f32_16x16x32_bf16 v[96:99], v[44:47], v[4:7], v[48:51]
	v_mfma_f32_16x16x32_bf16 v[40:43], v[40:43], v[8:11], 0
	v_mfma_f32_16x16x32_bf16 v[164:167], v[44:47], v[12:15], v[40:43]
	ds_read_b64_tr_b16 v[68:69], v221 offset:9216
	ds_read_b64_tr_b16 v[60:61], v221 offset:9248
	ds_read_b64_tr_b16 v[64:65], v221 offset:9280
	ds_read_b64_tr_b16 v[56:57], v221 offset:9312
	ds_read_b64_tr_b16 v[70:71], v221 offset:11520
	ds_read_b64_tr_b16 v[62:63], v221 offset:11552
	ds_read_b64_tr_b16 v[66:67], v221 offset:11584
	ds_read_b64_tr_b16 v[58:59], v221 offset:11616
	ds_read_b64_tr_b16 v[52:53], v221 offset:13824
	ds_read_b64_tr_b16 v[48:49], v221 offset:13856
	ds_read_b64_tr_b16 v[44:45], v221 offset:13888
	ds_read_b64_tr_b16 v[40:41], v221 offset:13920
	ds_read_b64_tr_b16 v[54:55], v221 offset:16128
	ds_read_b64_tr_b16 v[50:51], v221 offset:16160
	ds_read_b64_tr_b16 v[46:47], v221 offset:16192
	ds_read_b64_tr_b16 v[42:43], v221 offset:16224
	s_cmp_eq_u32 s99, 0
	s_cbranch_scc1 .Lfox1_nm0
	s_barrier
; DI float ex2(float x) { return __builtin_amdgcn_exp2f(x); }
; DI float shx(float v, int m, int lane) { return __int_as_float(__builtin_amdgcn_ds_bpermute((lane ^ m) << 2, __float_as_int(v))); }
; template <bool DIAG>
; DI void fox_tile(const bf16_t* sK, const bf16_t* sV, const float* sFk, const bf16x8 (&qf)[2][2], f32x4 (&o)[2][4], float (&mrun)[2], float (&lsum)[2], int key0, int qg0, int fr, int fq, int lane) {
;     ...
;   for (int mi = 0; mi < 2; ++mi) {
;     float mx = -INFINITY;
; #pragma unroll
;     for (int t = 0; t < 4; ++t)
; #pragma unroll
;       for (int j = 0; j < 4; ++j) {
;         float x = __builtin_fmaf(s[mi][t][j], SC2, fk[t][j]);
;         if (DIAG) { if (key0 + 16 * t + 4 * fq + j > qg0 + 16 * mi) x = -INFINITY; }
;         s[mi][t][j] = x; mx = fmaxf(mx, x);
;       }
;     mx = fmaxf(mx, shx(mx, 16, lane)); mx = fmaxf(mx, shx(mx, 32, lane));
;     const float mnew = fmaxf(mrun[mi], mx), alpha = ex2(mrun[mi] - mnew);
;     mrun[mi] = mnew;
;     float ps = 0.f;
; #pragma unroll
;     for (int t = 0; t < 4; ++t)
; #pragma unroll
;       for (int j = 0; j < 4; ++j) { const float pv = ex2(s[mi][t][j] - mnew); s[mi][t][j] = pv; ps += pv; }
.Lfox1_nm0:
	s_waitcnt lgkmcnt(14)
	v_fmamk_f32 v72, v72, 0x3e38aa3b, v36
	v_fmamk_f32 v73, v73, 0x3e38aa3b, v37
	s_mov_b32 s4, 0xff800000
	v_max3_f32 v100, v72, s4, v73
	v_fmamk_f32 v74, v74, 0x3e38aa3b, v38
	v_fmamk_f32 v75, v75, 0x3e38aa3b, v39
	v_max3_f32 v100, v100, v74, v75
	v_fmamk_f32 v101, v76, 0x3e38aa3b, v32
	v_fmamk_f32 v77, v77, 0x3e38aa3b, v33
	v_max3_f32 v76, v100, v101, v77
	v_fmamk_f32 v100, v78, 0x3e38aa3b, v34
	v_fmamk_f32 v79, v79, 0x3e38aa3b, v35
	v_max3_f32 v76, v76, v100, v79
	v_fmamk_f32 v102, v80, 0x3e38aa3b, v28
	v_fmamk_f32 v81, v81, 0x3e38aa3b, v29
	v_max3_f32 v76, v76, v102, v81
	v_fmamk_f32 v103, v82, 0x3e38aa3b, v30
	v_fmamk_f32 v83, v83, 0x3e38aa3b, v31
	v_max3_f32 v76, v76, v103, v83
	v_fmamk_f32 v96, v96, 0x3e38aa3b, v24
	v_fmamk_f32 v97, v97, 0x3e38aa3b, v25
	v_max3_f32 v76, v76, v96, v97
	v_fmamk_f32 v98, v98, 0x3e38aa3b, v26
	v_fmamk_f32 v99, v99, 0x3e38aa3b, v27
	v_max3_f32 v76, v76, v98, v99
	ds_bpermute_b32 v78, v204, v76
	v_fmamk_f32 v36, v84, 0x3e38aa3b, v36
	v_fmamk_f32 v37, v85, 0x3e38aa3b, v37
	v_fmamk_f32 v38, v86, 0x3e38aa3b, v38
	v_fmac_f32_e32 v39, 0x3e38aa3b, v87
	s_waitcnt lgkmcnt(0)
	v_max_f32_e32 v78, v78, v78
	v_max_f32_e32 v76, v76, v78
	ds_bpermute_b32 v78, v169, v76
	v_fmamk_f32 v32, v88, 0x3e38aa3b, v32
	v_fmamk_f32 v33, v89, 0x3e38aa3b, v33
	v_fmamk_f32 v34, v90, 0x3e38aa3b, v34
	v_fmac_f32_e32 v35, 0x3e38aa3b, v91
	s_waitcnt lgkmcnt(0)
	v_max3_f32 v220, v219, v76, v78
	v_sub_f32_e32 v73, v73, v220
	v_exp_f32_e32 v76, v73
	v_sub_f32_e32 v73, v74, v220
	v_exp_f32_e32 v74, v73
	v_sub_f32_e32 v73, v75, v220
	v_exp_f32_e32 v78, v73
	v_sub_f32_e32 v73, v101, v220
	v_exp_f32_e32 v82, v73
	v_sub_f32_e32 v73, v77, v220
	v_exp_f32_e32 v80, v73
	v_sub_f32_e32 v73, v100, v220
	v_exp_f32_e32 v100, v73
	v_sub_f32_e32 v73, v79, v220
	v_exp_f32_e32 v104, v73
	v_sub_f32_e32 v73, v102, v220
	v_exp_f32_e32 v102, v73
	v_sub_f32_e32 v73, v81, v220
	v_exp_f32_e32 v106, v73
	v_sub_f32_e32 v73, v103, v220
	v_exp_f32_e32 v148, v73
	v_sub_f32_e32 v73, v83, v220
	v_exp_f32_e32 v146, v73
	v_sub_f32_e32 v73, v96, v220
	v_exp_f32_e32 v150, v73
	v_sub_f32_e32 v73, v97, v220
	v_exp_f32_e32 v154, v73
	v_sub_f32_e32 v73, v98, v220
	v_exp_f32_e32 v152, v73
	v_sub_f32_e32 v73, v99, v220
	v_exp_f32_e32 v158, v73
	v_max3_f32 v73, v36, s4, v37
	v_max3_f32 v73, v73, v38, v39
	v_max3_f32 v73, v73, v32, v33
	v_max3_f32 v73, v73, v34, v35
	v_fmamk_f32 v28, v92, 0x3e38aa3b, v28
	v_fmamk_f32 v29, v93, 0x3e38aa3b, v29
	v_max3_f32 v73, v73, v28, v29
	v_fmamk_f32 v30, v94, 0x3e38aa3b, v30
	v_fmac_f32_e32 v31, 0x3e38aa3b, v95
	v_max3_f32 v73, v73, v30, v31
	v_fmamk_f32 v24, v164, 0x3e38aa3b, v24
	v_fmamk_f32 v25, v165, 0x3e38aa3b, v25
	v_max3_f32 v73, v73, v24, v25
	v_fmamk_f32 v26, v166, 0x3e38aa3b, v26
	v_fmac_f32_e32 v27, 0x3e38aa3b, v167
	v_max3_f32 v73, v73, v26, v27
	ds_bpermute_b32 v75, v204, v73
	v_sub_f32_e32 v105, v219, v220
	v_exp_f32_e32 v156, v105
	v_sub_f32_e32 v72, v72, v220
	v_exp_f32_e32 v72, v72
	s_waitcnt lgkmcnt(0)
	v_max_f32_e32 v75, v75, v75
	v_max_f32_e32 v73, v73, v75
	ds_bpermute_b32 v75, v169, v73
	v_pk_mul_f32 v[86:87], v[144:145], v[156:157] op_sel_hi:[1,0]
	v_pk_mul_f32 v[84:85], v[142:143], v[156:157] op_sel_hi:[1,0]
	v_pk_mul_f32 v[90:91], v[140:141], v[156:157] op_sel_hi:[1,0]
	v_pk_mul_f32 v[88:89], v[138:139], v[156:157] op_sel_hi:[1,0]
	s_waitcnt lgkmcnt(0)
; DI unsigned pk2(float lo, float hi) { unsigned r; asm volatile("v_cvt_pk_bf16_f32 %0, %1, %2" : "=v"(r) : "v"(lo), "v"(hi)); return r; }
; DI float ex2(float x) { return __builtin_amdgcn_exp2f(x); }
; DI f32x4 mmaT(bf16x8 a_m, bf16x8 b_n, f32x4 c) { return __builtin_amdgcn_mfma_f32_16x16x32_bf16(b_n, a_m, c, 0, 0, 0); }
; template <bool DIAG>
; DI void fox_tile(const bf16_t* sK, const bf16_t* sV, const float* sFk, const bf16x8 (&qf)[2][2], f32x4 (&o)[2][4], float (&mrun)[2], float (&lsum)[2], int key0, int qg0, int fr, int fq, int lane) {
;     ...
;     const float mnew = fmaxf(mrun[mi], mx), alpha = ex2(mrun[mi] - mnew);
;     mrun[mi] = mnew;
;     float ps = 0.f;
; #pragma unroll
;     for (int t = 0; t < 4; ++t)
; #pragma unroll
;       for (int j = 0; j < 4; ++j) { const float pv = ex2(s[mi][t][j] - mnew); s[mi][t][j] = pv; ps += pv; }
;     lsum[mi] = lsum[mi] * alpha + ps;
; #pragma unroll
;     for (int d = 0; d < 4; ++d) o[mi][d] *= alpha;
;   }
; #pragma unroll
;   for (int k2 = 0; k2 < 2; ++k2) {
;     bf16x8 pa[2];
; #pragma unroll
;     for (int mi = 0; mi < 2; ++mi) pa[mi] = mk8(pk2(s[mi][2 * k2][0], s[mi][2 * k2][1]), pk2(s[mi][2 * k2][2], s[mi][2 * k2][3]), pk2(s[mi][2 * k2 + 1][0], s[mi][2 * k2 + 1][1]), pk2(s[mi][2 * k2 + 1][2], s[mi][2 * k2 + 1][3]));
; #pragma unroll
;     for (int d = 0; d < 4; ++d) {
; #pragma unroll
;       for (int mi = 0; mi < 2; ++mi) o[mi][d] = mmaT(pa[mi], vf[k2][d], o[mi][d]);
;     }
	v_max3_f32 v222, v218, v73, v75
	v_sub_f32_e32 v103, v218, v222
	v_pk_mul_f32 v[94:95], v[136:137], v[156:157] op_sel_hi:[1,0]
	v_pk_mul_f32 v[92:93], v[134:135], v[156:157] op_sel_hi:[1,0]
	v_pk_mul_f32 v[98:99], v[132:133], v[156:157] op_sel_hi:[1,0]
	v_pk_mul_f32 v[96:97], v[130:131], v[156:157] op_sel_hi:[1,0]
	v_exp_f32_e32 v157, v103
	v_sub_f32_e32 v32, v32, v222
	v_sub_f32_e32 v36, v36, v222
	v_exp_f32_e32 v83, v32
	v_sub_f32_e32 v32, v33, v222
	v_exp_f32_e32 v73, v36
	v_sub_f32_e32 v36, v37, v222
	v_exp_f32_e32 v81, v32
	v_sub_f32_e32 v32, v34, v222
	v_exp_f32_e32 v77, v36
	v_sub_f32_e32 v36, v38, v222
	v_exp_f32_e32 v101, v32
	v_sub_f32_e32 v32, v35, v222
	v_mov_b32_e32 v130, v157
	v_exp_f32_e32 v75, v36
	v_sub_f32_e32 v36, v39, v222
	v_exp_f32_e32 v105, v32
	v_sub_f32_e32 v28, v28, v222
	v_pk_mul_f32 v[34:35], v[124:125], v[130:131] op_sel_hi:[1,0]
	v_pk_mul_f32 v[32:33], v[122:123], v[130:131] op_sel_hi:[1,0]
	v_exp_f32_e32 v79, v36
	v_exp_f32_e32 v103, v28
	v_sub_f32_e32 v28, v29, v222
	v_cvt_pk_bf16_f32 v36, v72, v76
	v_cvt_pk_bf16_f32 v37, v74, v78
	v_cvt_pk_bf16_f32 v38, v82, v80
	v_cvt_pk_bf16_f32 v39, v100, v104
	v_cvt_pk_bf16_f32 v122, v73, v77
	v_cvt_pk_bf16_f32 v123, v75, v79
	v_cvt_pk_bf16_f32 v124, v83, v81
	v_cvt_pk_bf16_f32 v125, v101, v105
	v_sub_f32_e32 v24, v24, v222
	v_mfma_f32_16x16x32_bf16 v[32:35], v[68:71], v[122:125], v[32:35]
	v_exp_f32_e32 v107, v28
	v_sub_f32_e32 v28, v30, v222
	v_exp_f32_e32 v151, v24
	v_mfma_f32_16x16x32_bf16 v[84:87], v[68:71], v[36:39], v[84:87]
	v_sub_f32_e32 v68, v31, v222
	v_sub_f32_e32 v24, v25, v222
	v_exp_f32_e32 v149, v28
	v_mfma_f32_16x16x32_bf16 v[28:31], v[60:63], v[36:39], v[88:91]
	v_exp_f32_e32 v147, v68
	v_pk_mul_f32 v[70:71], v[120:121], v[130:131] op_sel_hi:[1,0]
	v_pk_mul_f32 v[68:69], v[118:119], v[130:131] op_sel_hi:[1,0]
	v_exp_f32_e32 v155, v24
	v_pk_mul_f32 v[90:91], v[116:117], v[130:131] op_sel_hi:[1,0]
	v_pk_mul_f32 v[88:89], v[114:115], v[130:131] op_sel_hi:[1,0]
	v_sub_f32_e32 v24, v26, v222
	v_mfma_f32_16x16x32_bf16 v[60:63], v[60:63], v[122:125], v[68:71]
	v_exp_f32_e32 v153, v24
	v_mfma_f32_16x16x32_bf16 v[68:71], v[64:67], v[36:39], v[92:95]
	v_mfma_f32_16x16x32_bf16 v[64:67], v[64:67], v[122:125], v[88:91]
	s_nop 2
	v_sub_f32_e32 v88, v27, v222
	v_mfma_f32_16x16x32_bf16 v[24:27], v[56:59], v[36:39], v[96:99]
	v_mul_f32_e64 v38, v112, v130
	v_mul_f32_e64 v39, v113, v130
	v_pk_mul_f32 v[36:37], v[110:111], v[130:131] op_sel_hi:[1,0]
	v_exp_f32_e32 v159, v88
	s_nop 0
	v_mfma_f32_16x16x32_bf16 v[36:39], v[56:59], v[122:125], v[36:39]
	v_cvt_pk_bf16_f32 v56, v102, v106
	v_cvt_pk_bf16_f32 v57, v148, v146
	v_cvt_pk_bf16_f32 v58, v150, v154
	v_cvt_pk_bf16_f32 v59, v152, v158
	v_cvt_pk_bf16_f32 v110, v103, v107
	v_cvt_pk_bf16_f32 v111, v149, v147
	v_cvt_pk_bf16_f32 v112, v151, v155
	v_cvt_pk_bf16_f32 v113, v153, v159
	s_nop 0
	v_mfma_f32_16x16x32_bf16 v[92:95], v[52:55], v[110:113], v[32:35]
	s_nop 2
	v_add_f32_e64 v32, v72, 0
	v_add_f32_e64 v33, v73, 0
	v_mfma_f32_16x16x32_bf16 v[88:91], v[52:55], v[56:59], v[84:87]
	v_add_f32_e64 v32, v76, v32
	v_add_f32_e64 v33, v77, v33
	v_mfma_f32_16x16x32_bf16 v[84:87], v[48:51], v[56:59], v[28:31]
	s_nop 2
	v_add_f32_e64 v28, v74, v32
	v_add_f32_e64 v29, v75, v33
	v_mfma_f32_16x16x32_bf16 v[96:99], v[48:51], v[110:113], v[60:63]
	v_add_f32_e64 v28, v78, v28
	v_add_f32_e64 v29, v79, v29
	v_pk_add_f32 v[28:29], v[82:83], v[28:29]
	v_mfma_f32_16x16x32_bf16 v[76:79], v[40:43], v[56:59], v[24:27]
	v_add_f32_e64 v28, v80, v28
	v_add_f32_e64 v29, v81, v29
	v_pk_add_f32 v[28:29], v[100:101], v[28:29]
	v_mfma_f32_16x16x32_bf16 v[80:83], v[44:47], v[56:59], v[68:71]
	v_add_f32_e64 v28, v104, v28
	v_add_f32_e64 v29, v105, v29
	v_pk_add_f32 v[28:29], v[102:103], v[28:29]
	v_mfma_f32_16x16x32_bf16 v[100:103], v[44:47], v[110:113], v[64:67]
	v_add_f32_e64 v28, v106, v28
	v_add_f32_e64 v29, v107, v29
	v_pk_add_f32 v[28:29], v[148:149], v[28:29]
	v_mfma_f32_16x16x32_bf16 v[72:75], v[40:43], v[110:113], v[36:39]
	v_add_f32_e64 v28, v146, v28
	v_add_f32_e64 v29, v147, v29
	v_pk_add_f32 v[28:29], v[150:151], v[28:29]
	s_nop 0
	v_pk_add_f32 v[28:29], v[154:155], v[28:29]
	s_nop 0
	v_pk_add_f32 v[24:25], v[152:153], v[28:29]
	s_nop 0
	v_pk_add_f32 v[24:25], v[158:159], v[24:25]
	s_nop 0
	v_pk_fma_f32 v[104:105], v[128:129], v[156:157], v[24:25]
	v_mul_f32_e32 v224, 0xc0b17218, v220
	v_mul_f32_e32 v228, 0xc0b17218, v222
	v_mov_b32_e32 v225, v224
	v_mov_b32_e32 v229, v228
	v_mov_b32_e32 v226, v224
	v_mov_b32_e32 v230, v228
	v_mov_b32_e32 v227, v224
	v_mov_b32_e32 v231, v228

; DI void fox_unit(const Params& p, int hf, int bl, int fh, int qb, unsigned char* shm, int tid, bool dry = false) {
;     ...
;     if (kt + 1 < nkt) {
;       bf16_t* nK = (bf16_t*)(shm + (st ^ 1) * STG); bf16_t* nV = nK + 64 * 72; float* nF = (float*)(nV + 64 * 72);
;       *(uint4*)((unsigned char*)nK + kst) = kreg; *(uint4*)(nV + skey * 72 + sdg * 8) = vreg;
;       if (tid < 64) nF[tid] = freg;
;     }
;     __syncthreads();
.LBB0_494:
	s_cmp_lg_u32 s99, 0
	s_cbranch_scc1 .LBB0_497
	s_add_i32 s4, s21, 1
	s_and_b32 s4, s4, 3
	s_mulk_i32 s4, 0x4900
	s_add_i32 s12, s4, 32
	s_waitcnt lgkmcnt(0)
	v_add_u32_e32 v24, s12, v210
	s_waitcnt vmcnt(0)
	ds_write_b128 v24, v[16:19]
	ds_write_b128 v24, v[196:199] offset:4096
	v_add3_u32 v24, s12, v211, v160
	ds_write_b128 v24, v[20:23] offset:9216
	ds_write_b64 v24, v[170:171] offset:13824
	ds_write_b32 v24, v162 offset:13832
	ds_write_b32 v24, v168 offset:13836
	s_and_saveexec_b64 s[4:5], s[0:1]
	v_sub_f32_e32 v208, v192, v208
	v_lshl_add_u32 v24, v205, 2, s12
	v_mul_f32_e32 v208, 0x3fb8aa3b, v208
	ds_write_b32 v24, v208 offset:18432
	s_or_b64 exec, exec, s[4:5]
.LBB0_497:
	s_andn2_b64 vcc, exec, s[10:11]
	s_add_i32 s18, s18, 64
	s_waitcnt lgkmcnt(0)
	s_cmp_lg_u32 s99, 0
	s_cbranch_scc1 .Lfox1_nb
	s_barrier
.Lfox1_nb:
	s_cbranch_vccz .LBB0_634
	s_mov_b32 s22, s20
	s_branch .LBB0_483

; DI void fox_unit(const Params& p, int hf, int bl, int fh, int qb, unsigned char* shm, int tid, bool dry = false) {
;     ...
;   const float kmax2 = ((const float*)(wsb + WS_KMAX))[bl * 8 + fh];
;   const float thr = -110.0f - 0.25f * sqrtf(qm2 * kmax2) * 1.02f;
;   const int nkt = 4 * qb + 4;
;   int skip = 0;
;   if (tid < 4 * qb) skip = (Fref - F[tid * 64 + 63] < thr) ? 1 : 0;
;   const unsigned long long bal = __builtin_amdgcn_ballot_w64(skip != 0);
;   if (lane == 0) ((int*)sRed)[8 + wid] = __builtin_popcountll(bal);
;   __syncthreads();
;   int kt0 = 0;
; #pragma unroll
;   for (int i = 0; i < 8; ++i) kt0 += ((const int*)sRed)[8 + i];
;   f32x4 o[2][4];
; #pragma unroll
;   for (int mi = 0; mi < 2; ++mi)
; #pragma unroll
;     for (int d = 0; d < 4; ++d) o[mi][d] = (f32x4){0.f, 0.f, 0.f, 0.f};
;   float mrun[2] = {-1e30f, -1e30f}, lsum[2] = {0.f, 0.f};
;   const int skey = tid >> 3, sdg = tid & 7;
;   const int kst = ((skey >> 4) * 2 + (sdg >> 2)) * 1024 + ((((skey & 15) * 64) + (sdg & 3) * 16) ^ (((skey >> 3) & 1) << 5));
;   uint4 kreg, vreg; float freg = 0.f;
;   {
;     const size_t r = (size_t)(kt0 * 64 + skey) * NP;
;     kreg = *(const uint4*)(projb + r + C_FK + fh * 64 + sdg * 8); vreg = *(const uint4*)(projb + r + C_FV + fh * 64 + sdg * 8);
;     if (tid < 64) freg = (Fref - F[kt0 * 64 + tid]) * LOG2E;
;   }
;   {
;     bf16_t* sK = (bf16_t*)(shm + (kt0 & 1) * STG); bf16_t* sV = sK + 64 * 72; float* sFk = (float*)(sV + 64 * 72);
;     *(uint4*)((unsigned char*)sK + kst) = kreg; *(uint4*)(sV + skey * 72 + sdg * 8) = vreg;
;     if (tid < 64) sFk[tid] = freg;
;   }
;   __syncthreads();
.LBB0_593:
	s_or_b64 exec, exec, s[10:11]
	v_cndmask_b32_e64 v17, 0, 1, s[4:5]
	v_cmp_ne_u32_e64 s[0:1], 0, v17
	s_and_saveexec_b64 s[4:5], vcc
	s_bcnt1_i32_b64 s0, s[0:1]
	v_mov_b32_e32 v17, s0
	ds_write_b32 v16, v17 offset:37408
	s_or_b64 exec, exec, s[4:5]
	s_waitcnt lgkmcnt(0)
	s_barrier
	ds_read_b128 v[16:19], v203 offset:37408
	ds_read_b128 v[20:23], v203 offset:37424
	v_ashrrev_i32_e32 v25, 3, v205
	v_and_b32_e32 v29, 7, v205
	v_lshlrev_b32_e32 v160, 4, v29
	s_waitcnt lgkmcnt(1)
	v_readfirstlane_b32 s0, v16
	v_readfirstlane_b32 s1, v17
	v_readfirstlane_b32 s4, v18
	s_add_i32 s0, s1, s0
	v_readfirstlane_b32 s5, v19
	s_add_i32 s0, s0, s4
	s_waitcnt lgkmcnt(0)
	s_barrier
	v_readfirstlane_b32 s10, v20
	s_add_i32 s0, s0, s5
	v_readfirstlane_b32 s11, v21
	s_add_i32 s0, s0, s10
	v_readfirstlane_b32 s12, v22
	s_add_i32 s0, s0, s11
	v_readfirstlane_b32 s13, v23
	s_add_i32 s0, s0, s12
	s_add_i32 s21, s0, s13
	s_lshl_b32 s17, s21, 6
	v_add_u32_e32 v18, s17, v25
	v_mov_b64_e32 v[16:17], s[6:7]
	v_mad_i64_i32 v[16:17], s[0:1], v18, s65, v[16:17]
	v_lshl_add_u64 v[16:17], v[16:17], 0, s[2:3]
	v_lshl_add_u64 v[16:17], v[16:17], 0, v[160:161]
	v_add_co_u32_e32 v18, vcc, 0x1000, v16
	v_cmp_gt_i32_e64 s[0:1], 64, v205
	s_nop 0
	v_addc_co_u32_e32 v19, vcc, 0, v17, vcc
	v_add_co_u32_e32 v20, vcc, 0x2000, v16
	v_mov_b32_e32 v208, 0
	s_nop 0
	v_addc_co_u32_e32 v21, vcc, 0, v17, vcc
	global_load_dwordx4 v[16:19], v[18:19], off offset:3072
	s_nop 0
	global_load_dwordx4 v[20:23], v[20:21], off
	s_and_saveexec_b64 s[4:5], s[0:1]
	s_cbranch_execz .LBB0_597
	v_add_u32_e32 v30, s17, v205
	v_ashrrev_i32_e32 v31, 31, v30
	v_lshl_add_u64 v[30:31], v[30:31], 2, s[8:9]
	global_load_dword v30, v[30:31], off
	s_waitcnt vmcnt(0)
	v_sub_f32_e32 v30, v192, v30
	v_mul_f32_e32 v208, 0x3fb8aa3b, v30
.LBB0_597:
	s_or_b64 exec, exec, s[4:5]
	v_lshlrev_b32_e32 v30, 3, v29
	v_lshrrev_b32_e32 v29, 2, v29
	s_mov_b32 s4, 0x3ffffe
	v_lshlrev_b32_e32 v31, 4, v205
	v_and_or_b32 v26, v26, s4, v29
	v_lshlrev_b32_e32 v29, 6, v25
	v_and_b32_e32 v31, 48, v31
	s_movk_i32 s4, 0x3c0
	v_and_or_b32 v29, v29, s4, v31
	v_lshrrev_b32_e32 v31, 1, v205
	s_and_b32 s4, s21, 3
	v_lshlrev_b32_e32 v26, 10, v26
	v_and_b32_e32 v31, 32, v31
	s_mulk_i32 s4, 0x4900
	v_bitop3_b32 v210, v29, v26, v31 bitop3:0xde
	s_add_i32 s10, s4, 32
	v_add_u32_e32 v26, s10, v210
	s_movk_i32 s4, 0x48
	s_waitcnt vmcnt(1)
	ds_write_b128 v26, v[16:19]
	v_mul_lo_u32 v26, v25, s4
	v_lshlrev_b32_e32 v211, 1, v26
	v_lshlrev_b32_e32 v160, 1, v30
	v_add3_u32 v26, s10, v211, v160
	s_waitcnt vmcnt(0)
	ds_write_b128 v26, v[20:23] offset:9216
	s_and_saveexec_b64 s[4:5], s[0:1]
	v_lshl_add_u32 v26, v205, 2, s10
	ds_write_b32 v26, v208 offset:18432
	s_or_b64 exec, exec, s[4:5]
	v_bfe_u32 v29, v205, 4, 2
	s_add_i32 s18, s16, 4
	s_mov_b64 s[4:5], -1
	s_cmp_lt_i32 s21, s18
	v_lshlrev_b32_e32 v209, 2, v29
	s_waitcnt lgkmcnt(0)
	s_barrier
	s_cbranch_scc1 .LBB0_601
	v_lshlrev_b32_e32 v26, 2, v29
	s_mov_b64 s[4:5], 0

; DI void fox_unit(const Params& p, int hf, int bl, int fh, int qb, unsigned char* shm, int tid, bool dry = false) {
;     ...
;   for (int kt = kt0; kt < nkt; ++kt) {
;     const int st = kt & 1;
;     if (kt + 1 < nkt) {
.LBB0_603:
	s_add_i32 s19, s21, 1
	s_cmp_lt_i32 s19, s18
	s_cselect_b64 s[12:13], -1, 0
	s_cmp_ge_i32 s19, s18
	s_cselect_b64 s[10:11], -1, 0
	s_and_b64 vcc, exec, s[10:11]
	s_cbranch_vccz .LBB0_606
	s_and_b32 s20, s21, 3
	v_cmp_le_i32_e32 vcc, s17, v212
	s_and_saveexec_b64 s[14:15], vcc
	s_cbranch_execnz .LBB0_609

; DI void fox_unit(const Params& p, int hf, int bl, int fh, int qb, unsigned char* shm, int tid, bool dry = false) {
;     ...
;     if (kt + 1 < nkt) {
;       const size_t r = (size_t)((kt + 1) * 64 + skey) * NP;
;       kreg = *(const uint4*)(projb + r + C_FK + fh * 64 + sdg * 8); vreg = *(const uint4*)(projb + r + C_FV + fh * 64 + sdg * 8);
;       if (tid < 64) freg = (Fref - F[(kt + 1) * 64 + tid]) * LOG2E;
;     }
.LBB0_606:
	s_cmp_lg_u32 s99, 0
	s_cbranch_scc1 .Lfox2_noload
	v_add_u32_e32 v18, s17, v217
	v_mov_b64_e32 v[16:17], s[6:7]
	v_mad_i64_i32 v[16:17], s[4:5], v18, s65, v[16:17]
	v_lshl_add_u64 v[16:17], v[16:17], 0, s[2:3]
	v_lshl_add_u64 v[16:17], v[16:17], 0, v[160:161]
	v_add_co_u32_e32 v18, vcc, 0x1000, v16
	s_nop 1
	v_addc_co_u32_e32 v19, vcc, 0, v17, vcc
	v_add_co_u32_e32 v20, vcc, 0x2000, v16
	s_nop 1
	v_addc_co_u32_e32 v21, vcc, 0, v17, vcc
	s_mov_b32 s100, 0x68000
	s_mov_b32 s101, 0
	v_lshl_add_u64 v[100:101], v[18:19], 0, s[100:101]
	v_lshl_add_u64 v[102:103], v[20:21], 0, s[100:101]
	global_load_dwordx4 v[16:19], v[18:19], off offset:3072
	s_nop 0
	global_load_dwordx4 v[20:23], v[20:21], off
	global_load_dwordx4 v[196:199], v[100:101], off offset:3072
	global_load_dwordx2 v[170:171], v[102:103], off
	global_load_dword v162, v[102:103], off offset:8
	global_load_dword v168, v[102:103], off offset:12
	s_and_saveexec_b64 s[4:5], s[0:1]
	s_cbranch_execz .LBB0_608
	v_add_u32_e32 v24, s17, v216
	v_ashrrev_i32_e32 v25, 31, v24
	v_lshl_add_u64 v[24:25], v[24:25], 2, s[8:9]
	global_load_dword v208, v[24:25], off

; template <bool DIAG>
; DI void fox_tile(const bf16_t* sK, const bf16_t* sV, const float* sFk, const bf16x8 (&qf)[2][2], f32x4 (&o)[2][4], float (&mrun)[2], float (&lsum)[2], int key0, int qg0, int fr, int fq, int lane) {
;   const float SC2 = 0.125f * LOG2E;
;   f32x4 s[2][4];
;   const int kof = (fr * 64 + fq * 16) ^ ((fr >> 3) << 5);
; #pragma unroll
;   for (int t = 0; t < 4; ++t) {
;     const bf16x8 k0 = *(const bf16x8*)((const unsigned char*)sK + (t * 2) * 1024 + kof), k1 = *(const bf16x8*)((const unsigned char*)sK + (t * 2 + 1) * 1024 + kof);
; #pragma unroll
;     for (int mi = 0; mi < 2; ++mi) { s[mi][t] = mmaT(qf[mi][0], k0, (f32x4){0.f, 0.f, 0.f, 0.f}); s[mi][t] = mmaT(qf[mi][1], k1, s[mi][t]); }
;   }
;   f32x4 fk[4];
; #pragma unroll
;   for (int t = 0; t < 4; ++t) fk[t] = *(const f32x4*)(sFk + 16 * t + 4 * fq);
;   __builtin_amdgcn_sched_barrier(0);
;   bf16x8 vf[2][4];
; #pragma unroll
;   for (int k2 = 0; k2 < 2; ++k2)
; #pragma unroll
;     for (int d = 0; d < 4; ++d) {
;       const bf16_t* a = sV + (32 * k2 + 4 * fq + (fr >> 2)) * 72 + 16 * d + 4 * (fr & 3);
;       const v4i16_t lo = tr_rd(a), hi = tr_rd(a + 16 * 72);
;       vf[k2][d] = __builtin_shufflevector(lo, hi, 0, 1, 2, 3, 4, 5, 6, 7);
;     }
;   __builtin_amdgcn_sched_barrier(0);
; #pragma unroll
;   for (int mi = 0; mi < 2; ++mi) {
;     float mx = -INFINITY;
; #pragma unroll
;     for (int t = 0; t < 4; ++t)
; #pragma unroll
;       for (int j = 0; j < 4; ++j) {
;         float x = __builtin_fmaf(s[mi][t][j], SC2, fk[t][j]);
;         if (DIAG) { if (key0 + 16 * t + 4 * fq + j > qg0 + 16 * mi) x = -INFINITY; }
;         s[mi][t][j] = x; mx = fmaxf(mx, x);
; DI void fox_unit(const Params& p, int hf, int bl, int fh, int qb, unsigned char* shm, int tid, bool dry = false) {
;     ...
;     const int st = kt & 1;
;     if (kt + 1 < nkt) {
;       const size_t r = (size_t)((kt + 1) * 64 + skey) * NP;
;       kreg = *(const uint4*)(projb + r + C_FK + fh * 64 + sdg * 8); vreg = *(const uint4*)(projb + r + C_FV + fh * 64 + sdg * 8);
;       if (tid < 64) freg = (Fref - F[(kt + 1) * 64 + tid]) * LOG2E;
;     }
;     const bf16_t* sK = (const bf16_t*)(shm + st * STG); const bf16_t* sV = sK + 64 * 72; const float* sFk = (const float*)(sV + 64 * 72);
;     if (kt * 64 <= q0 + wid * 32 + 31) {
;       if (kt >= 4 * qb) fox_tile<true>(sK, sV, sFk, qf, o, mrun, lsum, kt * 64, qg0, fr, fq, lane);
.Lfox2_noload:
	s_and_b32 s20, s21, 3
	v_cmp_le_i32_e32 vcc, s17, v212
	s_and_saveexec_b64 s[14:15], vcc
	s_cbranch_execz .LBB0_605
.LBB0_609:
	s_mul_i32 s4, s20, 0x4900
	s_add_i32 s4, s4, 32
	v_add_u32_e32 v24, s4, v213
	ds_read_b128 v[64:67], v24
	ds_read_b128 v[68:71], v24 offset:1024
	ds_read_b128 v[56:59], v24 offset:2048
	ds_read_b128 v[60:63], v24 offset:3072
	ds_read_b128 v[48:51], v24 offset:4096
	ds_read_b128 v[52:55], v24 offset:5120
	ds_read_b128 v[40:43], v24 offset:6144
	ds_read_b128 v[44:47], v24 offset:7168
	v_lshl_add_u32 v24, v209, 2, s4
	ds_read_b128 v[36:39], v24 offset:18432
	ds_read_b128 v[32:35], v24 offset:18496
	ds_read_b128 v[28:31], v24 offset:18560
	ds_read_b128 v[24:27], v24 offset:18624
	v_lshl_add_u32 v72, v214, 1, s4
	s_cmp_lt_i32 s21, s16
	s_mov_b64 s[4:5], -1
	v_add_u32_e32 v221, v72, v215
	s_cbranch_scc1 .LBB0_611
	s_waitcnt lgkmcnt(11)
	v_mfma_f32_16x16x32_bf16 v[72:75], v[64:67], v[0:3], 0
	s_waitcnt lgkmcnt(10)
	v_mfma_f32_16x16x32_bf16 v[146:149], v[68:71], v[4:7], v[72:75]
	v_mfma_f32_16x16x32_bf16 v[72:75], v[64:67], v[8:11], 0
	v_mfma_f32_16x16x32_bf16 v[222:225], v[68:71], v[12:15], v[72:75]
	s_waitcnt lgkmcnt(9)
	v_mfma_f32_16x16x32_bf16 v[72:75], v[56:59], v[0:3], 0
	s_waitcnt lgkmcnt(8)
	v_mfma_f32_16x16x32_bf16 v[150:153], v[60:63], v[4:7], v[72:75]
	v_mfma_f32_16x16x32_bf16 v[72:75], v[56:59], v[8:11], 0
	v_mfma_f32_16x16x32_bf16 v[226:229], v[60:63], v[12:15], v[72:75]
	s_waitcnt lgkmcnt(7)
	v_mfma_f32_16x16x32_bf16 v[72:75], v[48:51], v[0:3], 0
	s_waitcnt lgkmcnt(6)
	v_mfma_f32_16x16x32_bf16 v[154:157], v[52:55], v[4:7], v[72:75]
	v_mfma_f32_16x16x32_bf16 v[72:75], v[48:51], v[8:11], 0
	v_mfma_f32_16x16x32_bf16 v[230:233], v[52:55], v[12:15], v[72:75]
	s_waitcnt lgkmcnt(5)
	v_mfma_f32_16x16x32_bf16 v[72:75], v[40:43], v[0:3], 0
	s_waitcnt lgkmcnt(4)
	v_mfma_f32_16x16x32_bf16 v[172:175], v[44:47], v[4:7], v[72:75]
	v_mfma_f32_16x16x32_bf16 v[72:75], v[40:43], v[8:11], 0
	v_mfma_f32_16x16x32_bf16 v[104:107], v[44:47], v[12:15], v[72:75]
	ds_read_b64_tr_b16 v[100:101], v221 offset:9216
	ds_read_b64_tr_b16 v[92:93], v221 offset:9248
	ds_read_b64_tr_b16 v[96:97], v221 offset:9280
	ds_read_b64_tr_b16 v[88:89], v221 offset:9312
	ds_read_b64_tr_b16 v[102:103], v221 offset:11520
	ds_read_b64_tr_b16 v[94:95], v221 offset:11552
	ds_read_b64_tr_b16 v[98:99], v221 offset:11584
	ds_read_b64_tr_b16 v[90:91], v221 offset:11616
	ds_read_b64_tr_b16 v[84:85], v221 offset:13824
	ds_read_b64_tr_b16 v[80:81], v221 offset:13856
	ds_read_b64_tr_b16 v[76:77], v221 offset:13888
	ds_read_b64_tr_b16 v[72:73], v221 offset:13920
	ds_read_b64_tr_b16 v[86:87], v221 offset:16128
	ds_read_b64_tr_b16 v[82:83], v221 offset:16160
	ds_read_b64_tr_b16 v[78:79], v221 offset:16192
	ds_read_b64_tr_b16 v[74:75], v221 offset:16224
	s_cmp_eq_u32 s99, 0
	s_cbranch_scc1 .Lfox2_nm1
	s_barrier
.Lfox2_nm1:
	v_add_u32_e32 v159, s17, v209
	s_waitcnt lgkmcnt(14)
	v_fmamk_f32 v147, v147, 0x3e38aa3b, v37
	v_cmp_lt_i32_e64 s[4:5], v159, v206
	v_add_u32_e32 v164, 2, v159
	v_fmamk_f32 v148, v148, 0x3e38aa3b, v38
	v_cndmask_b32_e64 v147, v200, v147, s[4:5]
	v_cmp_le_i32_e64 s[4:5], v164, v206
	v_add_u32_e32 v165, 3, v159
	v_fmamk_f32 v149, v149, 0x3e38aa3b, v39
	v_cndmask_b32_e64 v148, v200, v148, s[4:5]
	v_cmp_le_i32_e64 s[4:5], v165, v206
	v_add_u32_e32 v166, 16, v159
	v_fmamk_f32 v146, v146, 0x3e38aa3b, v36
	v_cmp_gt_i32_e32 vcc, v159, v206
	v_cndmask_b32_e64 v149, v200, v149, s[4:5]
	v_fmamk_f32 v150, v150, 0x3e38aa3b, v32
	v_cmp_le_i32_e64 s[4:5], v166, v206
	v_cndmask_b32_e32 v146, v146, v200, vcc
	s_mov_b32 s21, 0xff800000
	v_cndmask_b32_e64 v166, v200, v150, s[4:5]
	v_fmamk_f32 v150, v151, 0x3e38aa3b, v33
	v_add_u32_e32 v151, 17, v159
	v_max3_f32 v158, v146, s21, v147
	v_cmp_le_i32_e64 s[4:5], v151, v206
	v_add_u32_e32 v177, 18, v159
	v_max3_f32 v158, v158, v148, v149
	v_cndmask_b32_e64 v167, v200, v150, s[4:5]
	v_fmamk_f32 v152, v152, 0x3e38aa3b, v34
	v_cmp_le_i32_e64 s[4:5], v177, v206
	v_max3_f32 v150, v158, v166, v167
	v_add_u32_e32 v179, 32, v159
	v_cndmask_b32_e64 v158, v200, v152, s[4:5]
	v_fmamk_f32 v152, v153, 0x3e38aa3b, v35
	v_add_u32_e32 v153, 19, v159
	v_cmp_le_i32_e64 s[4:5], v153, v206
	v_add_u32_e32 v181, 34, v159
	v_add_u32_e32 v185, 48, v159
	v_cndmask_b32_e64 v176, v200, v152, s[4:5]
	v_fmamk_f32 v152, v154, 0x3e38aa3b, v28
	v_cmp_le_i32_e64 s[4:5], v179, v206
	v_add_u32_e32 v187, 50, v159
	v_max3_f32 v150, v150, v158, v176
	v_cndmask_b32_e64 v178, v200, v152, s[4:5]
	v_fmamk_f32 v152, v155, 0x3e38aa3b, v29
	v_add_u32_e32 v155, 33, v159
	v_cmp_le_i32_e64 s[4:5], v155, v206
	v_fmamk_f32 v104, v104, 0x3e38aa3b, v24
	s_nop 0
	v_cndmask_b32_e64 v180, v200, v152, s[4:5]
	v_fmamk_f32 v152, v156, 0x3e38aa3b, v30
	v_cmp_le_i32_e64 s[4:5], v181, v206
	v_max3_f32 v150, v150, v178, v180
	s_nop 0
	v_cndmask_b32_e64 v182, v200, v152, s[4:5]
	v_fmamk_f32 v152, v157, 0x3e38aa3b, v31
	v_add_u32_e32 v157, 35, v159
	v_cmp_le_i32_e64 s[4:5], v157, v206
	s_nop 1
	v_cndmask_b32_e64 v183, v200, v152, s[4:5]
	v_fmamk_f32 v152, v172, 0x3e38aa3b, v24
	v_cmp_le_i32_e64 s[4:5], v185, v206
	v_max3_f32 v150, v150, v182, v183
	s_nop 0
	v_cndmask_b32_e64 v184, v200, v152, s[4:5]
	v_fmamk_f32 v152, v173, 0x3e38aa3b, v25
	v_add_u32_e32 v173, 49, v159
	v_cmp_le_i32_e64 s[4:5], v173, v206
	s_nop 1
	v_cndmask_b32_e64 v186, v200, v152, s[4:5]
	v_fmamk_f32 v152, v174, 0x3e38aa3b, v26
	v_cmp_le_i32_e64 s[4:5], v187, v206
	v_max3_f32 v150, v150, v184, v186
	s_nop 0
	v_cndmask_b32_e64 v188, v200, v152, s[4:5]
	v_fmamk_f32 v152, v175, 0x3e38aa3b, v27
	v_add_u32_e32 v175, 51, v159
	v_cmp_le_i32_e64 s[4:5], v175, v206
	s_nop 1
	v_cndmask_b32_e64 v189, v200, v152, s[4:5]
	v_max3_f32 v150, v150, v188, v189
	ds_bpermute_b32 v152, v204, v150
	v_cmp_le_i32_e64 s[4:5], v159, v207
	s_waitcnt lgkmcnt(0)
; DI float ex2(float x) { return __builtin_amdgcn_exp2f(x); }
; DI float shx(float v, int m, int lane) { return __int_as_float(__builtin_amdgcn_ds_bpermute((lane ^ m) << 2, __float_as_int(v))); }
; template <bool DIAG>
; DI void fox_tile(const bf16_t* sK, const bf16_t* sV, const float* sFk, const bf16x8 (&qf)[2][2], f32x4 (&o)[2][4], float (&mrun)[2], float (&lsum)[2], int key0, int qg0, int fr, int fq, int lane) {
;     ...
;   for (int mi = 0; mi < 2; ++mi) {
;     float mx = -INFINITY;
; #pragma unroll
;     for (int t = 0; t < 4; ++t)
; #pragma unroll
;       for (int j = 0; j < 4; ++j) {
;         float x = __builtin_fmaf(s[mi][t][j], SC2, fk[t][j]);
;         if (DIAG) { if (key0 + 16 * t + 4 * fq + j > qg0 + 16 * mi) x = -INFINITY; }
;         s[mi][t][j] = x; mx = fmaxf(mx, x);
;       }
;     mx = fmaxf(mx, shx(mx, 16, lane)); mx = fmaxf(mx, shx(mx, 32, lane));
;     const float mnew = fmaxf(mrun[mi], mx), alpha = ex2(mrun[mi] - mnew);
;     mrun[mi] = mnew;
;     float ps = 0.f;
; #pragma unroll
;     for (int t = 0; t < 4; ++t)
; #pragma unroll
;       for (int j = 0; j < 4; ++j) { const float pv = ex2(s[mi][t][j] - mnew); s[mi][t][j] = pv; ps += pv; }
;     lsum[mi] = lsum[mi] * alpha + ps;
; #pragma unroll
;     for (int d = 0; d < 4; ++d) o[mi][d] *= alpha;
;   }
	v_max_f32_e32 v152, v152, v152
	v_max_f32_e32 v150, v150, v152
	ds_bpermute_b32 v152, v169, v150
	s_waitcnt lgkmcnt(0)
	v_max3_f32 v220, v219, v150, v152
	v_sub_f32_e32 v147, v147, v220
	v_exp_f32_e32 v150, v147
	v_sub_f32_e32 v147, v148, v220
	v_exp_f32_e32 v148, v147
	v_sub_f32_e32 v147, v149, v220
	v_exp_f32_e32 v152, v147
	v_sub_f32_e32 v147, v166, v220
	v_exp_f32_e32 v156, v147
	v_sub_f32_e32 v147, v167, v220
	v_exp_f32_e32 v154, v147
	v_sub_f32_e32 v147, v158, v220
	v_exp_f32_e32 v158, v147
	v_sub_f32_e32 v147, v176, v220
	v_exp_f32_e32 v174, v147
	v_sub_f32_e32 v147, v178, v220
	v_exp_f32_e32 v172, v147
	v_sub_f32_e32 v147, v180, v220
	v_exp_f32_e32 v176, v147
	v_sub_f32_e32 v147, v182, v220
	v_exp_f32_e32 v180, v147
	v_sub_f32_e32 v147, v183, v220
	v_exp_f32_e32 v178, v147
	v_sub_f32_e32 v147, v184, v220
	v_exp_f32_e32 v182, v147
	v_sub_f32_e32 v147, v186, v220
	v_exp_f32_e32 v186, v147
	v_sub_f32_e32 v147, v188, v220
	v_exp_f32_e32 v184, v147
	v_sub_f32_e32 v147, v189, v220
	v_exp_f32_e32 v190, v147
	v_fmamk_f32 v147, v222, 0x3e38aa3b, v36
	v_cndmask_b32_e64 v147, v200, v147, s[4:5]
	v_fmamk_f32 v149, v223, 0x3e38aa3b, v37
	v_cmp_lt_i32_e64 s[4:5], v159, v207
	v_fmamk_f32 v166, v224, 0x3e38aa3b, v38
	v_fmamk_f32 v167, v227, 0x3e38aa3b, v33
	v_cndmask_b32_e64 v149, v200, v149, s[4:5]
	v_cmp_le_i32_e64 s[4:5], v164, v207
	v_max3_f32 v159, v147, s21, v149
	v_sub_f32_e32 v191, v219, v220
	v_cndmask_b32_e64 v164, v200, v166, s[4:5]
	v_fmamk_f32 v166, v225, 0x3e38aa3b, v39
	v_cmp_le_i32_e64 s[4:5], v165, v207
	v_exp_f32_e32 v188, v191
	v_sub_f32_e32 v146, v146, v220
	v_cndmask_b32_e64 v165, v200, v166, s[4:5]
	v_fmamk_f32 v166, v226, 0x3e38aa3b, v32
	v_cndmask_b32_e32 v166, v166, v200, vcc
	v_cmp_le_i32_e32 vcc, v151, v207
	v_max3_f32 v159, v159, v164, v165
	v_pk_mul_f32 v[226:227], v[140:141], v[188:189] op_sel_hi:[1,0]
	v_cndmask_b32_e32 v167, v200, v167, vcc
	v_max3_f32 v151, v159, v166, v167
	v_fmamk_f32 v159, v228, 0x3e38aa3b, v34
	v_cmp_le_i32_e32 vcc, v177, v207
	v_fmamk_f32 v177, v229, 0x3e38aa3b, v35
	v_pk_mul_f32 v[224:225], v[138:139], v[188:189] op_sel_hi:[1,0]
	v_cndmask_b32_e32 v159, v200, v159, vcc
	v_cmp_le_i32_e32 vcc, v153, v207
	v_fmamk_f32 v153, v230, 0x3e38aa3b, v28
	v_pk_mul_f32 v[228:229], v[134:135], v[188:189] op_sel_hi:[1,0]
	v_cndmask_b32_e32 v177, v200, v177, vcc
	v_cmp_le_i32_e32 vcc, v179, v207
	v_max3_f32 v151, v151, v159, v177
	v_pk_mul_f32 v[234:235], v[132:133], v[188:189] op_sel_hi:[1,0]
	v_cndmask_b32_e32 v179, v200, v153, vcc
	v_fmamk_f32 v153, v231, 0x3e38aa3b, v29
	v_cmp_le_i32_e32 vcc, v155, v207
	v_pk_mul_f32 v[230:231], v[136:137], v[188:189] op_sel_hi:[1,0]
	v_exp_f32_e32 v146, v146
	v_cndmask_b32_e32 v183, v200, v153, vcc
	v_fmamk_f32 v153, v232, 0x3e38aa3b, v30
	v_cmp_le_i32_e32 vcc, v181, v207
	v_max3_f32 v151, v151, v179, v183
	v_cvt_pk_bf16_f32 v240, v146, v150
	v_cvt_pk_bf16_f32 v241, v148, v152
	v_cvt_pk_bf16_f32 v242, v156, v154
	v_cvt_pk_bf16_f32 v243, v158, v174
	s_nop 0
	v_cndmask_b32_e32 v181, v200, v153, vcc
	v_fmamk_f32 v153, v233, 0x3e38aa3b, v31
	v_cmp_le_i32_e32 vcc, v157, v207
	v_pk_mul_f32 v[232:233], v[130:131], v[188:189] op_sel_hi:[1,0]
	v_mfma_f32_16x16x32_bf16 v[224:227], v[92:95], v[240:243], v[224:227]
	v_cndmask_b32_e32 v191, v200, v153, vcc
	v_cmp_le_i32_e32 vcc, v185, v207
	v_max3_f32 v151, v151, v181, v191
	v_mfma_f32_16x16x32_bf16 v[228:231], v[96:99], v[240:243], v[228:231]
	v_cndmask_b32_e32 v185, v200, v104, vcc
	v_fmamk_f32 v104, v105, 0x3e38aa3b, v25
	v_cmp_le_i32_e32 vcc, v173, v207
	v_fmamk_f32 v105, v106, 0x3e38aa3b, v26
	v_mfma_f32_16x16x32_bf16 v[232:235], v[88:91], v[240:243], v[232:235]
	v_cndmask_b32_e32 v223, v200, v104, vcc
	v_cmp_le_i32_e32 vcc, v187, v207
	v_max3_f32 v104, v151, v185, v223
	s_mov_b64 s[4:5], 0
	v_cndmask_b32_e32 v194, v200, v105, vcc
	v_fmamk_f32 v105, v107, 0x3e38aa3b, v27
	v_cmp_le_i32_e32 vcc, v175, v207
	v_pk_mul_f32 v[106:107], v[144:145], v[188:189] op_sel_hi:[1,0]
	s_nop 0
	v_cndmask_b32_e32 v202, v200, v105, vcc
	v_max3_f32 v151, v104, v194, v202
	ds_bpermute_b32 v153, v204, v151
	v_pk_mul_f32 v[104:105], v[142:143], v[188:189] op_sel_hi:[1,0]
	s_waitcnt lgkmcnt(0)
; DI unsigned pk2(float lo, float hi) { unsigned r; asm volatile("v_cvt_pk_bf16_f32 %0, %1, %2" : "=v"(r) : "v"(lo), "v"(hi)); return r; }
; DI f32x4 mmaT(bf16x8 a_m, bf16x8 b_n, f32x4 c) { return __builtin_amdgcn_mfma_f32_16x16x32_bf16(b_n, a_m, c, 0, 0, 0); }
; template <bool DIAG>
; DI void fox_tile(const bf16_t* sK, const bf16_t* sV, const float* sFk, const bf16x8 (&qf)[2][2], f32x4 (&o)[2][4], float (&mrun)[2], float (&lsum)[2], int key0, int qg0, int fr, int fq, int lane) {
;     ...
; #pragma unroll
;   for (int k2 = 0; k2 < 2; ++k2) {
;     bf16x8 pa[2];
; #pragma unroll
;     for (int mi = 0; mi < 2; ++mi) pa[mi] = mk8(pk2(s[mi][2 * k2][0], s[mi][2 * k2][1]), pk2(s[mi][2 * k2][2], s[mi][2 * k2][3]), pk2(s[mi][2 * k2 + 1][0], s[mi][2 * k2 + 1][1]), pk2(s[mi][2 * k2 + 1][2], s[mi][2 * k2 + 1][3]));
; #pragma unroll
;     for (int d = 0; d < 4; ++d) {
; #pragma unroll
;       for (int mi = 0; mi < 2; ++mi) o[mi][d] = mmaT(pa[mi], vf[k2][d], o[mi][d]);
;     }
;   }
	v_max_f32_e32 v153, v153, v153
	v_max_f32_e32 v151, v151, v153
	ds_bpermute_b32 v153, v169, v151
	v_mfma_f32_16x16x32_bf16 v[104:107], v[100:103], v[240:243], v[104:107]
	s_waitcnt lgkmcnt(0)
	v_max3_f32 v222, v218, v151, v153
	v_sub_f32_e32 v173, v218, v222
	v_sub_f32_e32 v149, v149, v222
	v_exp_f32_e32 v189, v173
	v_exp_f32_e32 v151, v149
	v_sub_f32_e32 v149, v164, v222
	v_sub_f32_e32 v164, v177, v222
	v_exp_f32_e32 v175, v164
	v_sub_f32_e32 v164, v179, v222
	v_exp_f32_e32 v173, v164
	v_sub_f32_e32 v164, v183, v222
	v_exp_f32_e32 v177, v164
	v_mov_b32_e32 v164, v189
	v_sub_f32_e32 v153, v165, v222
	v_sub_f32_e32 v155, v166, v222
	v_pk_mul_f32 v[238:239], v[124:125], v[164:165] op_sel_hi:[1,0]
	v_pk_mul_f32 v[236:237], v[122:123], v[164:165] op_sel_hi:[1,0]
	v_sub_f32_e32 v165, v181, v222
	v_sub_f32_e32 v147, v147, v222
	v_exp_f32_e32 v157, v155
	v_sub_f32_e32 v155, v167, v222
	v_sub_f32_e32 v159, v159, v222
	v_exp_f32_e32 v181, v165
	v_sub_f32_e32 v165, v191, v222
	v_exp_f32_e32 v147, v147
	v_exp_f32_e32 v149, v149
	v_exp_f32_e32 v153, v153
	v_exp_f32_e32 v155, v155
	v_exp_f32_e32 v159, v159
	v_cvt_pk_bf16_f32 v244, v147, v151
	v_cvt_pk_bf16_f32 v245, v149, v153
	v_cvt_pk_bf16_f32 v246, v157, v155
	v_cvt_pk_bf16_f32 v247, v159, v175
	v_exp_f32_e32 v179, v165
	v_mfma_f32_16x16x32_bf16 v[100:103], v[100:103], v[244:247], v[236:239]
	s_nop 2
	v_mul_f32_e64 v238, v120, v164
	v_mul_f32_e64 v239, v121, v164
	v_pk_mul_f32 v[236:237], v[118:119], v[164:165] op_sel_hi:[1,0]
	s_nop 1
	v_mfma_f32_16x16x32_bf16 v[236:239], v[92:95], v[244:247], v[236:239]
	v_sub_f32_e32 v92, v185, v222
	v_exp_f32_e32 v183, v92
	v_sub_f32_e32 v92, v223, v222
	v_exp_f32_e32 v187, v92
	v_pk_mul_f32 v[94:95], v[116:117], v[164:165] op_sel_hi:[1,0]
	v_pk_mul_f32 v[92:93], v[114:115], v[164:165] op_sel_hi:[1,0]
	s_nop 1
	v_mfma_f32_16x16x32_bf16 v[248:251], v[96:99], v[244:247], v[92:95]
	s_nop 2
	v_sub_f32_e32 v92, v194, v222
	v_exp_f32_e32 v185, v92
	v_sub_f32_e32 v92, v202, v222
	v_exp_f32_e32 v191, v92
	v_pk_mul_f32 v[94:95], v[112:113], v[164:165] op_sel_hi:[1,0]
	v_pk_mul_f32 v[92:93], v[110:111], v[164:165] op_sel_hi:[1,0]
	s_nop 1
	v_mfma_f32_16x16x32_bf16 v[240:243], v[88:91], v[244:247], v[92:95]
	v_cvt_pk_bf16_f32 v244, v172, v176
	v_cvt_pk_bf16_f32 v245, v180, v178
	v_cvt_pk_bf16_f32 v246, v182, v186
	v_cvt_pk_bf16_f32 v247, v184, v190
	v_cvt_pk_bf16_f32 v164, v173, v177
	v_cvt_pk_bf16_f32 v165, v181, v179
	v_cvt_pk_bf16_f32 v166, v183, v187
	v_cvt_pk_bf16_f32 v167, v185, v191
	s_nop 0
	v_mfma_f32_16x16x32_bf16 v[88:91], v[84:87], v[244:247], v[104:107]
	v_mfma_f32_16x16x32_bf16 v[92:95], v[84:87], v[164:167], v[100:103]
	v_add_f32_e64 v84, v146, 0
	v_add_f32_e64 v85, v147, 0
	v_pk_add_f32 v[96:97], v[150:151], v[84:85]
	v_mfma_f32_16x16x32_bf16 v[84:87], v[80:83], v[244:247], v[224:227]
	v_add_f32_e64 v96, v148, v96
	v_add_f32_e64 v97, v149, v97
	v_pk_add_f32 v[96:97], v[152:153], v[96:97]
	s_nop 0
	v_pk_add_f32 v[100:101], v[156:157], v[96:97]
	v_mfma_f32_16x16x32_bf16 v[96:99], v[80:83], v[164:167], v[236:239]
	v_add_f32_e64 v80, v154, v100
	v_add_f32_e64 v81, v155, v101
	v_pk_add_f32 v[80:81], v[158:159], v[80:81]
	s_nop 0
	v_pk_add_f32 v[100:101], v[174:175], v[80:81]
	v_mfma_f32_16x16x32_bf16 v[80:83], v[76:79], v[244:247], v[228:231]
	v_add_f32_e64 v100, v172, v100
	v_add_f32_e64 v101, v173, v101
	v_pk_add_f32 v[100:101], v[176:177], v[100:101]
	s_nop 0
	v_pk_add_f32 v[104:105], v[180:181], v[100:101]
	v_mfma_f32_16x16x32_bf16 v[100:103], v[76:79], v[164:167], v[248:251]
	v_add_f32_e64 v76, v178, v104
	v_add_f32_e64 v77, v179, v105
	v_pk_add_f32 v[76:77], v[182:183], v[76:77]
	s_nop 0
	v_pk_add_f32 v[104:105], v[186:187], v[76:77]
	v_mfma_f32_16x16x32_bf16 v[76:79], v[72:75], v[244:247], v[232:235]
	v_add_f32_e64 v104, v184, v104
	v_add_f32_e64 v105, v185, v105
	v_pk_add_f32 v[104:105], v[190:191], v[104:105]
	v_mfma_f32_16x16x32_bf16 v[72:75], v[72:75], v[164:167], v[240:243]
	v_fma_f32 v104, v128, v188, v104
	v_fma_f32 v105, v129, v189, v105

; DI void fox_unit(const Params& p, int hf, int bl, int fh, int qb, unsigned char* shm, int tid, bool dry = false) {
;     ...
;     if (kt + 1 < nkt) {
;       bf16_t* nK = (bf16_t*)(shm + (st ^ 1) * STG); bf16_t* nV = nK + 64 * 72; float* nF = (float*)(nV + 64 * 72);
;       *(uint4*)((unsigned char*)nK + kst) = kreg; *(uint4*)(nV + skey * 72 + sdg * 8) = vreg;
;       if (tid < 64) nF[tid] = freg;
;     }
;     __syncthreads();
.LBB0_614:
	s_cmp_lg_u32 s99, 0
	s_cbranch_scc1 .LBB0_617
	s_add_i32 s4, s20, 1
	s_and_b32 s4, s4, 3
	s_mulk_i32 s4, 0x4900
	s_add_i32 s12, s4, 32
	s_waitcnt lgkmcnt(0)
	v_add_u32_e32 v24, s12, v210
	s_waitcnt vmcnt(0)
	ds_write_b128 v24, v[16:19]
	ds_write_b128 v24, v[196:199] offset:4096
	v_add3_u32 v24, s12, v211, v160
	ds_write_b128 v24, v[20:23] offset:9216
	ds_write_b64 v24, v[170:171] offset:13824
	ds_write_b32 v24, v162 offset:13832
	ds_write_b32 v24, v168 offset:13836
	s_and_saveexec_b64 s[4:5], s[0:1]
	v_sub_f32_e32 v208, v192, v208
	v_lshl_add_u32 v24, v205, 2, s12
	v_mul_f32_e32 v208, 0x3fb8aa3b, v208
	ds_write_b32 v24, v208 offset:18432
	s_or_b64 exec, exec, s[4:5]
.LBB0_617:
	s_andn2_b64 vcc, exec, s[10:11]
	s_add_i32 s17, s17, 64
	s_waitcnt lgkmcnt(0)
	s_cmp_lg_u32 s99, 0
	s_cbranch_scc1 .Lfox2_nb
	s_barrier
.Lfox2_nb:
	s_cbranch_vccz .LBB0_619
	s_mov_b32 s21, s19
	s_branch .LBB0_603

; DI unsigned pk2(float lo, float hi) { unsigned r; asm volatile("v_cvt_pk_bf16_f32 %0, %1, %2" : "=v"(r) : "v"(lo), "v"(hi)); return r; }
; DI float bflo(unsigned u) { return __uint_as_float(u << 16); }
; DI float bfhi(unsigned u) { return __uint_as_float(u & 0xffff0000u); }
; DI float silu_f(float x) { return x * __builtin_amdgcn_rcpf(1.0f + __expf(-x)); }
; DI float shx(float v, int m, int lane) { return __int_as_float(__builtin_amdgcn_ds_bpermute((lane ^ m) << 2, __float_as_int(v))); }
; DI void fox_unit(const Params& p, int hf, int bl, int fh, int qb, unsigned char* shm, int tid, bool dry = false) {
;     ...
; #pragma unroll
;   for (int mi = 0; mi < 2; ++mi) {
;     float l = lsum[mi]; l += shx(l, 16, lane); l += shx(l, 32, lane);
;     const float inv = 1.0f / l;
;     bf16_t* gp = projb + (size_t)(qg0 + 16 * mi) * NP + C_FG + fh * 64 + 4 * fq;
; #pragma unroll
;     for (int d = 0; d < 4; ++d) {
;       const uint2 gv = *(const uint2*)(gp + 16 * d);
;       uint2 w;
;       w.x = pk2(o[mi][d][0] * inv * silu_f(bflo(gv.x)), o[mi][d][1] * inv * silu_f(bfhi(gv.x)));
;       w.y = pk2(o[mi][d][2] * inv * silu_f(bflo(gv.y)), o[mi][d][3] * inv * silu_f(bfhi(gv.y)));
;       if (!dry || inv == 1.2345e-30f) *(uint2*)(gp + 16 * d) = w;
;     }
.LBB0_620:
	ds_bpermute_b32 v0, v204, v128
	v_mov_b32_e32 v27, v161
	s_mov_b64 s[6:7], 0x3000
	s_movk_i32 s4, 0x3000
	s_waitcnt lgkmcnt(0)
	v_add_f32_e32 v0, v128, v0
	ds_bpermute_b32 v1, v169, v0
	s_waitcnt lgkmcnt(0)
	v_add_f32_e32 v0, v0, v1
	v_div_scale_f32 v1, s[0:1], v0, v0, 1.0
	v_rcp_f32_e32 v2, v1
	s_nop 0
	v_fma_f32 v3, -v1, v2, 1.0
	v_fmac_f32_e32 v2, v3, v2
	v_div_scale_f32 v3, vcc, 1.0, v0, 1.0
	v_mul_f32_e32 v4, v3, v2
	v_fma_f32 v5, -v1, v4, v3
	v_fmac_f32_e32 v4, v5, v2
	v_fma_f32 v1, -v1, v4, v3
	v_div_fmas_f32 v1, v1, v2, v4
	v_div_fixup_f32 v6, v1, v0, 1.0
	v_lshl_add_u64 v[2:3], v[126:127], 0, s[2:3]
	v_lshlrev_b64 v[0:1], 1, v[26:27]
	v_lshl_add_u64 v[4:5], v[2:3], 0, v[0:1]
	v_lshl_add_u64 v[2:3], v[4:5], 0, s[6:7]
	v_add_co_u32_e32 v4, vcc, s4, v4
	v_mul_f32_e32 v7, v142, v6
	s_nop 0
	v_addc_co_u32_e32 v5, vcc, 0, v5, vcc
	global_load_dwordx2 v[8:9], v[4:5], off
	s_waitcnt vmcnt(0)
	v_lshlrev_b32_e32 v10, 16, v8
	v_mul_f32_e32 v11, 0xbfb8aa3b, v10
	v_exp_f32_e32 v11, v11
	v_and_b32_e32 v8, 0xffff0000, v8
	v_add_f32_e32 v11, 1.0, v11
	v_rcp_f32_e32 v11, v11
	s_nop 0
	v_mul_f32_e32 v10, v11, v10
	v_mul_f32_e32 v11, 0xbfb8aa3b, v8
	v_exp_f32_e32 v11, v11
	v_mul_f32_e32 v7, v7, v10
	v_mul_f32_e32 v10, v143, v6
	v_add_f32_e32 v11, 1.0, v11
	v_rcp_f32_e32 v11, v11
	s_nop 0
	v_mul_f32_e32 v8, v11, v8
	v_mul_f32_e32 v8, v10, v8
	v_lshlrev_b32_e32 v10, 16, v9
	v_mul_f32_e32 v11, 0xbfb8aa3b, v10
	v_exp_f32_e32 v11, v11
	v_and_b32_e32 v9, 0xffff0000, v9
	v_cvt_pk_bf16_f32 v8, v7, v8
	v_mul_f32_e32 v7, v144, v6
	v_add_f32_e32 v11, 1.0, v11
	v_rcp_f32_e32 v11, v11
	s_nop 0
	v_mul_f32_e32 v10, v11, v10
	v_mul_f32_e32 v11, 0xbfb8aa3b, v9
	v_exp_f32_e32 v11, v11
	v_mul_f32_e32 v7, v7, v10
	v_mul_f32_e32 v10, v145, v6
	v_add_f32_e32 v11, 1.0, v11
	v_rcp_f32_e32 v11, v11
	s_nop 0
	v_mul_f32_e32 v9, v11, v9
	v_mul_f32_e32 v9, v10, v9
	v_cvt_pk_bf16_f32 v9, v7, v9
	global_store_dwordx2 v[4:5], v[8:9], off
	global_load_dwordx2 v[4:5], v[2:3], off offset:32
	v_mul_f32_e32 v7, v138, v6
	s_waitcnt vmcnt(0)
	v_lshlrev_b32_e32 v8, 16, v4
	v_mul_f32_e32 v9, 0xbfb8aa3b, v8
	v_exp_f32_e32 v9, v9
	v_and_b32_e32 v4, 0xffff0000, v4
	v_add_f32_e32 v9, 1.0, v9
	v_rcp_f32_e32 v9, v9
	s_nop 0
	v_mul_f32_e32 v8, v9, v8
	v_mul_f32_e32 v9, 0xbfb8aa3b, v4
	v_exp_f32_e32 v9, v9
	v_mul_f32_e32 v7, v7, v8
	v_mul_f32_e32 v8, v139, v6
	v_add_f32_e32 v9, 1.0, v9
	v_rcp_f32_e32 v9, v9
	s_nop 0
	v_mul_f32_e32 v4, v9, v4
	v_mul_f32_e32 v4, v8, v4
	v_lshlrev_b32_e32 v8, 16, v5
	v_mul_f32_e32 v9, 0xbfb8aa3b, v8
	v_exp_f32_e32 v9, v9
	v_and_b32_e32 v5, 0xffff0000, v5
	v_cvt_pk_bf16_f32 v4, v7, v4
	v_mul_f32_e32 v7, v140, v6
	v_add_f32_e32 v9, 1.0, v9
	v_rcp_f32_e32 v9, v9
	s_nop 0
	v_mul_f32_e32 v8, v9, v8
	v_mul_f32_e32 v9, 0xbfb8aa3b, v5
	v_exp_f32_e32 v9, v9
	v_mul_f32_e32 v7, v7, v8
	v_mul_f32_e32 v8, v141, v6
	v_add_f32_e32 v9, 1.0, v9
	v_rcp_f32_e32 v9, v9
	s_nop 0
	v_mul_f32_e32 v5, v9, v5
	v_mul_f32_e32 v5, v8, v5
	v_cvt_pk_bf16_f32 v5, v7, v5
	global_store_dwordx2 v[2:3], v[4:5], off offset:32
	global_load_dwordx2 v[4:5], v[2:3], off offset:64
	v_mul_f32_e32 v7, v134, v6
	s_waitcnt vmcnt(0)
	v_lshlrev_b32_e32 v8, 16, v4
	v_mul_f32_e32 v9, 0xbfb8aa3b, v8
	v_exp_f32_e32 v9, v9
	v_and_b32_e32 v4, 0xffff0000, v4
	v_add_f32_e32 v9, 1.0, v9
	v_rcp_f32_e32 v9, v9
	s_nop 0
	v_mul_f32_e32 v8, v9, v8
	v_mul_f32_e32 v9, 0xbfb8aa3b, v4
	v_exp_f32_e32 v9, v9
	v_mul_f32_e32 v7, v7, v8
	v_mul_f32_e32 v8, v135, v6
	v_add_f32_e32 v9, 1.0, v9
	v_rcp_f32_e32 v9, v9
	s_nop 0
	v_mul_f32_e32 v4, v9, v4
	v_mul_f32_e32 v4, v8, v4
	v_lshlrev_b32_e32 v8, 16, v5
	v_mul_f32_e32 v9, 0xbfb8aa3b, v8
	v_exp_f32_e32 v9, v9
	v_and_b32_e32 v5, 0xffff0000, v5
	v_cvt_pk_bf16_f32 v4, v7, v4
	v_mul_f32_e32 v7, v136, v6
	v_add_f32_e32 v9, 1.0, v9
	v_rcp_f32_e32 v9, v9
	s_nop 0
	v_mul_f32_e32 v8, v9, v8
	v_mul_f32_e32 v9, 0xbfb8aa3b, v5
	v_exp_f32_e32 v9, v9
	v_mul_f32_e32 v7, v7, v8
	v_mul_f32_e32 v8, v137, v6
	v_add_f32_e32 v9, 1.0, v9
	v_rcp_f32_e32 v9, v9
	s_nop 0
	v_mul_f32_e32 v5, v9, v5
	v_mul_f32_e32 v5, v8, v5
	v_cvt_pk_bf16_f32 v5, v7, v5
	global_store_dwordx2 v[2:3], v[4:5], off offset:64
	global_load_dwordx2 v[4:5], v[2:3], off offset:96
	v_mul_f32_e32 v7, v130, v6
	s_waitcnt vmcnt(0)
	v_lshlrev_b32_e32 v8, 16, v4
	v_mul_f32_e32 v9, 0xbfb8aa3b, v8
	v_exp_f32_e32 v9, v9
	v_and_b32_e32 v4, 0xffff0000, v4
	v_add_f32_e32 v9, 1.0, v9
	v_rcp_f32_e32 v9, v9
	s_nop 0
	v_mul_f32_e32 v8, v9, v8
	v_mul_f32_e32 v9, 0xbfb8aa3b, v4
	v_exp_f32_e32 v9, v9
	v_mul_f32_e32 v7, v7, v8
	v_mul_f32_e32 v8, v131, v6
	v_add_f32_e32 v9, 1.0, v9
	v_rcp_f32_e32 v9, v9
	s_nop 0
	v_mul_f32_e32 v4, v9, v4
	v_mul_f32_e32 v4, v8, v4
	v_lshlrev_b32_e32 v8, 16, v5
	v_mul_f32_e32 v9, 0xbfb8aa3b, v8
	v_exp_f32_e32 v9, v9
	v_cvt_pk_bf16_f32 v4, v7, v4
	v_mul_f32_e32 v7, v132, v6
	v_and_b32_e32 v5, 0xffff0000, v5
	v_add_f32_e32 v9, 1.0, v9
	v_rcp_f32_e32 v9, v9
	v_mul_f32_e32 v6, v133, v6
	v_mul_f32_e32 v8, v9, v8
	v_mul_f32_e32 v7, v7, v8
	v_mul_f32_e32 v8, 0xbfb8aa3b, v5
	v_exp_f32_e32 v8, v8
	s_nop 0
	v_add_f32_e32 v8, 1.0, v8
	v_rcp_f32_e32 v8, v8
	s_nop 0
	v_mul_f32_e32 v5, v8, v5
	v_mul_f32_e32 v5, v6, v5
	v_cvt_pk_bf16_f32 v5, v7, v5
	global_store_dwordx2 v[2:3], v[4:5], off offset:96
	ds_bpermute_b32 v2, v204, v129
	s_waitcnt lgkmcnt(0)
; DI unsigned pk2(float lo, float hi) { unsigned r; asm volatile("v_cvt_pk_bf16_f32 %0, %1, %2" : "=v"(r) : "v"(lo), "v"(hi)); return r; }
; DI float bflo(unsigned u) { return __uint_as_float(u << 16); }
; DI float bfhi(unsigned u) { return __uint_as_float(u & 0xffff0000u); }
; DI float silu_f(float x) { return x * __builtin_amdgcn_rcpf(1.0f + __expf(-x)); }
; DI float shx(float v, int m, int lane) { return __int_as_float(__builtin_amdgcn_ds_bpermute((lane ^ m) << 2, __float_as_int(v))); }
; DI void fox_unit(const Params& p, int hf, int bl, int fh, int qb, unsigned char* shm, int tid, bool dry = false) {
;     ...
; #pragma unroll
;   for (int mi = 0; mi < 2; ++mi) {
;     float l = lsum[mi]; l += shx(l, 16, lane); l += shx(l, 32, lane);
;     const float inv = 1.0f / l;
;     bf16_t* gp = projb + (size_t)(qg0 + 16 * mi) * NP + C_FG + fh * 64 + 4 * fq;
; #pragma unroll
;     for (int d = 0; d < 4; ++d) {
;       const uint2 gv = *(const uint2*)(gp + 16 * d);
;       uint2 w;
;       w.x = pk2(o[mi][d][0] * inv * silu_f(bflo(gv.x)), o[mi][d][1] * inv * silu_f(bfhi(gv.x)));
;       w.y = pk2(o[mi][d][2] * inv * silu_f(bflo(gv.y)), o[mi][d][3] * inv * silu_f(bfhi(gv.y)));
;       if (!dry || inv == 1.2345e-30f) *(uint2*)(gp + 16 * d) = w;
;     }
;   }
	v_add_f32_e32 v2, v129, v2
	ds_bpermute_b32 v3, v169, v2
	s_waitcnt lgkmcnt(0)
	v_add_f32_e32 v2, v2, v3
	v_div_scale_f32 v3, s[0:1], v2, v2, 1.0
	v_rcp_f32_e32 v4, v3
	s_nop 0
	v_fma_f32 v5, -v3, v4, 1.0
	v_fmac_f32_e32 v4, v5, v4
	v_div_scale_f32 v5, vcc, 1.0, v2, 1.0
	v_mul_f32_e32 v6, v5, v4
	v_fma_f32 v7, -v3, v6, v5
	v_fmac_f32_e32 v6, v7, v4
	v_fma_f32 v3, -v3, v6, v5
	v_div_fmas_f32 v3, v3, v4, v6
	v_div_fixup_f32 v4, v3, v2, 1.0
	v_lshl_add_u64 v[2:3], v[108:109], 0, s[2:3]
	v_lshl_add_u64 v[2:3], v[2:3], 0, v[0:1]
	v_lshl_add_u64 v[0:1], v[2:3], 0, s[6:7]
	v_add_co_u32_e32 v2, vcc, s4, v2
	v_mul_f32_e32 v5, v122, v4
	s_nop 0
	v_addc_co_u32_e32 v3, vcc, 0, v3, vcc
	global_load_dwordx2 v[6:7], v[2:3], off
	v_readlane_b32 s6, v254, 55
	v_readlane_b32 s7, v254, 56
	s_waitcnt vmcnt(0)
	v_lshlrev_b32_e32 v8, 16, v6
	v_mul_f32_e32 v9, 0xbfb8aa3b, v8
	v_exp_f32_e32 v9, v9
	v_and_b32_e32 v6, 0xffff0000, v6
	v_add_f32_e32 v9, 1.0, v9
	v_rcp_f32_e32 v9, v9
	s_nop 0
	v_mul_f32_e32 v8, v9, v8
	v_mul_f32_e32 v9, 0xbfb8aa3b, v6
	v_exp_f32_e32 v9, v9
	v_mul_f32_e32 v5, v5, v8
	v_mul_f32_e32 v8, v123, v4
	v_add_f32_e32 v9, 1.0, v9
	v_rcp_f32_e32 v9, v9
	s_nop 0
	v_mul_f32_e32 v6, v9, v6
	v_mul_f32_e32 v6, v8, v6
	v_lshlrev_b32_e32 v8, 16, v7
	v_mul_f32_e32 v9, 0xbfb8aa3b, v8
	v_exp_f32_e32 v9, v9
	v_and_b32_e32 v7, 0xffff0000, v7
	v_cvt_pk_bf16_f32 v6, v5, v6
	v_mul_f32_e32 v5, v124, v4
	v_add_f32_e32 v9, 1.0, v9
	v_rcp_f32_e32 v9, v9
	s_nop 0
	v_mul_f32_e32 v8, v9, v8
	v_mul_f32_e32 v9, 0xbfb8aa3b, v7
	v_exp_f32_e32 v9, v9
	v_mul_f32_e32 v5, v5, v8
	v_mul_f32_e32 v8, v125, v4
	v_add_f32_e32 v9, 1.0, v9
	v_rcp_f32_e32 v9, v9
	s_nop 0
	v_mul_f32_e32 v7, v9, v7
	v_mul_f32_e32 v7, v8, v7
	v_cvt_pk_bf16_f32 v7, v5, v7
	global_store_dwordx2 v[2:3], v[6:7], off
	global_load_dwordx2 v[2:3], v[0:1], off offset:32
	v_mul_f32_e32 v5, v118, v4
	s_waitcnt vmcnt(0)
	v_lshlrev_b32_e32 v6, 16, v2
	v_mul_f32_e32 v7, 0xbfb8aa3b, v6
	v_exp_f32_e32 v7, v7
	v_and_b32_e32 v2, 0xffff0000, v2
	v_add_f32_e32 v7, 1.0, v7
	v_rcp_f32_e32 v7, v7
	s_nop 0
	v_mul_f32_e32 v6, v7, v6
	v_mul_f32_e32 v7, 0xbfb8aa3b, v2
	v_exp_f32_e32 v7, v7
	v_mul_f32_e32 v5, v5, v6
	v_mul_f32_e32 v6, v119, v4
	v_add_f32_e32 v7, 1.0, v7
	v_rcp_f32_e32 v7, v7
	s_nop 0
	v_mul_f32_e32 v2, v7, v2
	v_mul_f32_e32 v2, v6, v2
	v_lshlrev_b32_e32 v6, 16, v3
	v_mul_f32_e32 v7, 0xbfb8aa3b, v6
	v_exp_f32_e32 v7, v7
	v_and_b32_e32 v3, 0xffff0000, v3
	v_cvt_pk_bf16_f32 v2, v5, v2
	v_mul_f32_e32 v5, v120, v4
	v_add_f32_e32 v7, 1.0, v7
	v_rcp_f32_e32 v7, v7
	s_nop 0
	v_mul_f32_e32 v6, v7, v6
	v_mul_f32_e32 v7, 0xbfb8aa3b, v3
	v_exp_f32_e32 v7, v7
	v_mul_f32_e32 v5, v5, v6
	v_mul_f32_e32 v6, v121, v4
	v_add_f32_e32 v7, 1.0, v7
	v_rcp_f32_e32 v7, v7
	s_nop 0
	v_mul_f32_e32 v3, v7, v3
	v_mul_f32_e32 v3, v6, v3
	v_cvt_pk_bf16_f32 v3, v5, v3
	global_store_dwordx2 v[0:1], v[2:3], off offset:32
	global_load_dwordx2 v[2:3], v[0:1], off offset:64
	v_mul_f32_e32 v5, v114, v4
	s_waitcnt vmcnt(0)
	v_lshlrev_b32_e32 v6, 16, v2
	v_mul_f32_e32 v7, 0xbfb8aa3b, v6
	v_exp_f32_e32 v7, v7
	v_and_b32_e32 v2, 0xffff0000, v2
	v_add_f32_e32 v7, 1.0, v7
	v_rcp_f32_e32 v7, v7
	s_nop 0
	v_mul_f32_e32 v6, v7, v6
	v_mul_f32_e32 v7, 0xbfb8aa3b, v2
	v_exp_f32_e32 v7, v7
	v_mul_f32_e32 v5, v5, v6
	v_mul_f32_e32 v6, v115, v4
	v_add_f32_e32 v7, 1.0, v7
	v_rcp_f32_e32 v7, v7
	s_nop 0
	v_mul_f32_e32 v2, v7, v2
	v_mul_f32_e32 v2, v6, v2
	v_lshlrev_b32_e32 v6, 16, v3
	v_mul_f32_e32 v7, 0xbfb8aa3b, v6
	v_exp_f32_e32 v7, v7
	v_and_b32_e32 v3, 0xffff0000, v3
	v_cvt_pk_bf16_f32 v2, v5, v2
	v_mul_f32_e32 v5, v116, v4
	v_add_f32_e32 v7, 1.0, v7
	v_rcp_f32_e32 v7, v7
	s_nop 0
	v_mul_f32_e32 v6, v7, v6
	v_mul_f32_e32 v7, 0xbfb8aa3b, v3
	v_exp_f32_e32 v7, v7
	v_mul_f32_e32 v5, v5, v6
	v_mul_f32_e32 v6, v117, v4
	v_add_f32_e32 v7, 1.0, v7
	v_rcp_f32_e32 v7, v7
	s_nop 0
	v_mul_f32_e32 v3, v7, v3
	v_mul_f32_e32 v3, v6, v3
	v_cvt_pk_bf16_f32 v3, v5, v3
	global_store_dwordx2 v[0:1], v[2:3], off offset:64
	global_load_dwordx2 v[2:3], v[0:1], off offset:96
	v_mul_f32_e32 v5, v110, v4
	s_waitcnt vmcnt(0)
	v_lshlrev_b32_e32 v6, 16, v2
	v_mul_f32_e32 v7, 0xbfb8aa3b, v6
	v_exp_f32_e32 v7, v7
	v_and_b32_e32 v2, 0xffff0000, v2
	v_add_f32_e32 v7, 1.0, v7
	v_rcp_f32_e32 v7, v7
	s_nop 0
	v_mul_f32_e32 v6, v7, v6
	v_mul_f32_e32 v7, 0xbfb8aa3b, v2
	v_exp_f32_e32 v7, v7
	v_mul_f32_e32 v5, v5, v6
	v_mul_f32_e32 v6, v111, v4
	v_add_f32_e32 v7, 1.0, v7
	v_rcp_f32_e32 v7, v7
	s_nop 0
	v_mul_f32_e32 v2, v7, v2
	v_mul_f32_e32 v2, v6, v2
	v_lshlrev_b32_e32 v6, 16, v3
	v_mul_f32_e32 v7, 0xbfb8aa3b, v6
	v_exp_f32_e32 v7, v7
	v_cvt_pk_bf16_f32 v2, v5, v2
	v_mul_f32_e32 v5, v112, v4
	v_and_b32_e32 v3, 0xffff0000, v3
	v_add_f32_e32 v7, 1.0, v7
	v_rcp_f32_e32 v7, v7
	v_mul_f32_e32 v4, v113, v4
	v_mul_f32_e32 v6, v7, v6
	v_mul_f32_e32 v5, v5, v6
	v_mul_f32_e32 v6, 0xbfb8aa3b, v3
	v_exp_f32_e32 v6, v6
	s_nop 0
	v_add_f32_e32 v6, 1.0, v6
	v_rcp_f32_e32 v6, v6
	s_nop 0
	v_mul_f32_e32 v3, v6, v3
	v_mul_f32_e32 v3, v4, v3
	v_cvt_pk_bf16_f32 v3, v5, v3
	global_store_dwordx2 v[0:1], v[2:3], off offset:96
	v_mov_b32_e32 v162, 0x358637bd
	v_mov_b32_e32 v168, 0x3f317218
	v_mov_b64_e32 v[170:171], 0xff
	v_mov_b32_e32 v195, 0x3ecc95a3
	v_mov_b64_e32 v[196:197], 0x6bf
	v_mov_b32_e32 v198, 0x7f800000
	v_mov_b32_e32 v199, 0x7fc00000

; DI unsigned pk2(float lo, float hi) { unsigned r; asm volatile("v_cvt_pk_bf16_f32 %0, %1, %2" : "=v"(r) : "v"(lo), "v"(hi)); return r; }
; DI float bflo(unsigned u) { return __uint_as_float(u << 16); }
; DI float bfhi(unsigned u) { return __uint_as_float(u & 0xffff0000u); }
; DI float silu_f(float x) { return x * __builtin_amdgcn_rcpf(1.0f + __expf(-x)); }
; DI float shx(float v, int m, int lane) { return __int_as_float(__builtin_amdgcn_ds_bpermute((lane ^ m) << 2, __float_as_int(v))); }
; DI void fox_unit(const Params& p, int hf, int bl, int fh, int qb, unsigned char* shm, int tid, bool dry = false) {
;     ...
; #pragma unroll
;   for (int mi = 0; mi < 2; ++mi) {
;     float l = lsum[mi]; l += shx(l, 16, lane); l += shx(l, 32, lane);
;     const float inv = 1.0f / l;
;     bf16_t* gp = projb + (size_t)(qg0 + 16 * mi) * NP + C_FG + fh * 64 + 4 * fq;
; #pragma unroll
;     for (int d = 0; d < 4; ++d) {
;       const uint2 gv = *(const uint2*)(gp + 16 * d);
;       uint2 w;
;       w.x = pk2(o[mi][d][0] * inv * silu_f(bflo(gv.x)), o[mi][d][1] * inv * silu_f(bfhi(gv.x)));
;       w.y = pk2(o[mi][d][2] * inv * silu_f(bflo(gv.y)), o[mi][d][3] * inv * silu_f(bfhi(gv.y)));
;       if (!dry || inv == 1.2345e-30f) *(uint2*)(gp + 16 * d) = w;
;     }
.LBB0_635:
	ds_bpermute_b32 v0, v204, v128
	v_mov_b32_e32 v27, v161
	s_mov_b64 s[6:7], 0x3000
	s_movk_i32 s4, 0x3000
	s_waitcnt lgkmcnt(0)
	v_add_f32_e32 v0, v128, v0
	ds_bpermute_b32 v1, v169, v0
	s_waitcnt lgkmcnt(0)
	v_add_f32_e32 v0, v0, v1
	v_div_scale_f32 v1, s[0:1], v0, v0, 1.0
	v_rcp_f32_e32 v2, v1
	s_nop 0
	v_fma_f32 v3, -v1, v2, 1.0
	v_fmac_f32_e32 v2, v3, v2
	v_div_scale_f32 v3, vcc, 1.0, v0, 1.0
	v_mul_f32_e32 v4, v3, v2
	v_fma_f32 v5, -v1, v4, v3
	v_fmac_f32_e32 v4, v5, v2
	v_fma_f32 v1, -v1, v4, v3
	v_div_fmas_f32 v1, v1, v2, v4
	v_div_fixup_f32 v6, v1, v0, 1.0
	v_lshl_add_u64 v[2:3], v[126:127], 0, s[2:3]
	v_lshlrev_b64 v[0:1], 1, v[26:27]
	v_lshl_add_u64 v[4:5], v[2:3], 0, v[0:1]
	v_lshl_add_u64 v[2:3], v[4:5], 0, s[6:7]
	v_add_co_u32_e32 v4, vcc, s4, v4
	v_mul_f32_e32 v7, v142, v6
	s_nop 0
	v_addc_co_u32_e32 v5, vcc, 0, v5, vcc
	global_load_dwordx2 v[8:9], v[4:5], off
	s_waitcnt vmcnt(0)
	v_lshlrev_b32_e32 v10, 16, v8
	v_mul_f32_e32 v11, 0xbfb8aa3b, v10
	v_exp_f32_e32 v11, v11
	v_and_b32_e32 v8, 0xffff0000, v8
	v_add_f32_e32 v11, 1.0, v11
	v_rcp_f32_e32 v11, v11
	s_nop 0
	v_mul_f32_e32 v10, v11, v10
	v_mul_f32_e32 v11, 0xbfb8aa3b, v8
	v_exp_f32_e32 v11, v11
	v_mul_f32_e32 v7, v7, v10
	v_mul_f32_e32 v10, v143, v6
	v_add_f32_e32 v11, 1.0, v11
	v_rcp_f32_e32 v11, v11
	s_nop 0
	v_mul_f32_e32 v8, v11, v8
	v_mul_f32_e32 v8, v10, v8
	v_lshlrev_b32_e32 v10, 16, v9
	v_mul_f32_e32 v11, 0xbfb8aa3b, v10
	v_exp_f32_e32 v11, v11
	v_and_b32_e32 v9, 0xffff0000, v9
	v_cvt_pk_bf16_f32 v8, v7, v8
	v_mul_f32_e32 v7, v144, v6
	v_add_f32_e32 v11, 1.0, v11
	v_rcp_f32_e32 v11, v11
	s_nop 0
	v_mul_f32_e32 v10, v11, v10
	v_mul_f32_e32 v11, 0xbfb8aa3b, v9
	v_exp_f32_e32 v11, v11
	v_mul_f32_e32 v7, v7, v10
	v_mul_f32_e32 v10, v145, v6
	v_add_f32_e32 v11, 1.0, v11
	v_rcp_f32_e32 v11, v11
	s_nop 0
	v_mul_f32_e32 v9, v11, v9
	v_mul_f32_e32 v9, v10, v9
	v_cvt_pk_bf16_f32 v9, v7, v9
	global_store_dwordx2 v[4:5], v[8:9], off
	global_load_dwordx2 v[4:5], v[2:3], off offset:32
	v_mul_f32_e32 v7, v138, v6
	s_waitcnt vmcnt(0)
	v_lshlrev_b32_e32 v8, 16, v4
	v_mul_f32_e32 v9, 0xbfb8aa3b, v8
	v_exp_f32_e32 v9, v9
	v_and_b32_e32 v4, 0xffff0000, v4
	v_add_f32_e32 v9, 1.0, v9
	v_rcp_f32_e32 v9, v9
	s_nop 0
	v_mul_f32_e32 v8, v9, v8
	v_mul_f32_e32 v9, 0xbfb8aa3b, v4
	v_exp_f32_e32 v9, v9
	v_mul_f32_e32 v7, v7, v8
	v_mul_f32_e32 v8, v139, v6
	v_add_f32_e32 v9, 1.0, v9
	v_rcp_f32_e32 v9, v9
	s_nop 0
	v_mul_f32_e32 v4, v9, v4
	v_mul_f32_e32 v4, v8, v4
	v_lshlrev_b32_e32 v8, 16, v5
	v_mul_f32_e32 v9, 0xbfb8aa3b, v8
	v_exp_f32_e32 v9, v9
	v_and_b32_e32 v5, 0xffff0000, v5
	v_cvt_pk_bf16_f32 v4, v7, v4
	v_mul_f32_e32 v7, v140, v6
	v_add_f32_e32 v9, 1.0, v9
	v_rcp_f32_e32 v9, v9
	s_nop 0
	v_mul_f32_e32 v8, v9, v8
	v_mul_f32_e32 v9, 0xbfb8aa3b, v5
	v_exp_f32_e32 v9, v9
	v_mul_f32_e32 v7, v7, v8
	v_mul_f32_e32 v8, v141, v6
	v_add_f32_e32 v9, 1.0, v9
	v_rcp_f32_e32 v9, v9
	s_nop 0
	v_mul_f32_e32 v5, v9, v5
	v_mul_f32_e32 v5, v8, v5
	v_cvt_pk_bf16_f32 v5, v7, v5
	global_store_dwordx2 v[2:3], v[4:5], off offset:32
	global_load_dwordx2 v[4:5], v[2:3], off offset:64
	v_mul_f32_e32 v7, v134, v6
	s_waitcnt vmcnt(0)
	v_lshlrev_b32_e32 v8, 16, v4
	v_mul_f32_e32 v9, 0xbfb8aa3b, v8
	v_exp_f32_e32 v9, v9
	v_and_b32_e32 v4, 0xffff0000, v4
	v_add_f32_e32 v9, 1.0, v9
	v_rcp_f32_e32 v9, v9
	s_nop 0
	v_mul_f32_e32 v8, v9, v8
	v_mul_f32_e32 v9, 0xbfb8aa3b, v4
	v_exp_f32_e32 v9, v9
	v_mul_f32_e32 v7, v7, v8
	v_mul_f32_e32 v8, v135, v6
	v_add_f32_e32 v9, 1.0, v9
	v_rcp_f32_e32 v9, v9
	s_nop 0
	v_mul_f32_e32 v4, v9, v4
	v_mul_f32_e32 v4, v8, v4
	v_lshlrev_b32_e32 v8, 16, v5
	v_mul_f32_e32 v9, 0xbfb8aa3b, v8
	v_exp_f32_e32 v9, v9
	v_and_b32_e32 v5, 0xffff0000, v5
	v_cvt_pk_bf16_f32 v4, v7, v4
	v_mul_f32_e32 v7, v136, v6
	v_add_f32_e32 v9, 1.0, v9
	v_rcp_f32_e32 v9, v9
	s_nop 0
	v_mul_f32_e32 v8, v9, v8
	v_mul_f32_e32 v9, 0xbfb8aa3b, v5
	v_exp_f32_e32 v9, v9
	v_mul_f32_e32 v7, v7, v8
	v_mul_f32_e32 v8, v137, v6
	v_add_f32_e32 v9, 1.0, v9
	v_rcp_f32_e32 v9, v9
	s_nop 0
	v_mul_f32_e32 v5, v9, v5
	v_mul_f32_e32 v5, v8, v5
	v_cvt_pk_bf16_f32 v5, v7, v5
	global_store_dwordx2 v[2:3], v[4:5], off offset:64
	global_load_dwordx2 v[4:5], v[2:3], off offset:96
	v_mul_f32_e32 v7, v130, v6
	s_waitcnt vmcnt(0)
	v_lshlrev_b32_e32 v8, 16, v4
	v_mul_f32_e32 v9, 0xbfb8aa3b, v8
	v_exp_f32_e32 v9, v9
	v_and_b32_e32 v4, 0xffff0000, v4
	v_add_f32_e32 v9, 1.0, v9
	v_rcp_f32_e32 v9, v9
	s_nop 0
	v_mul_f32_e32 v8, v9, v8
	v_mul_f32_e32 v9, 0xbfb8aa3b, v4
	v_exp_f32_e32 v9, v9
	v_mul_f32_e32 v7, v7, v8
	v_mul_f32_e32 v8, v131, v6
	v_add_f32_e32 v9, 1.0, v9
	v_rcp_f32_e32 v9, v9
	s_nop 0
	v_mul_f32_e32 v4, v9, v4
	v_mul_f32_e32 v4, v8, v4
	v_lshlrev_b32_e32 v8, 16, v5
	v_mul_f32_e32 v9, 0xbfb8aa3b, v8
	v_exp_f32_e32 v9, v9
	v_cvt_pk_bf16_f32 v4, v7, v4
	v_mul_f32_e32 v7, v132, v6
	v_and_b32_e32 v5, 0xffff0000, v5
	v_add_f32_e32 v9, 1.0, v9
	v_rcp_f32_e32 v9, v9
	v_mul_f32_e32 v6, v133, v6
	v_mul_f32_e32 v8, v9, v8
	v_mul_f32_e32 v7, v7, v8
	v_mul_f32_e32 v8, 0xbfb8aa3b, v5
	v_exp_f32_e32 v8, v8
	s_nop 0
	v_add_f32_e32 v8, 1.0, v8
	v_rcp_f32_e32 v8, v8
	s_nop 0
	v_mul_f32_e32 v5, v8, v5
	v_mul_f32_e32 v5, v6, v5
	v_cvt_pk_bf16_f32 v5, v7, v5
	global_store_dwordx2 v[2:3], v[4:5], off offset:96
	ds_bpermute_b32 v2, v204, v129
	s_waitcnt lgkmcnt(0)
; DI unsigned pk2(float lo, float hi) { unsigned r; asm volatile("v_cvt_pk_bf16_f32 %0, %1, %2" : "=v"(r) : "v"(lo), "v"(hi)); return r; }
; DI float bflo(unsigned u) { return __uint_as_float(u << 16); }
; DI float bfhi(unsigned u) { return __uint_as_float(u & 0xffff0000u); }
; DI float silu_f(float x) { return x * __builtin_amdgcn_rcpf(1.0f + __expf(-x)); }
; DI float shx(float v, int m, int lane) { return __int_as_float(__builtin_amdgcn_ds_bpermute((lane ^ m) << 2, __float_as_int(v))); }
; DI void fox_unit(const Params& p, int hf, int bl, int fh, int qb, unsigned char* shm, int tid, bool dry = false) {
;     ...
; #pragma unroll
;   for (int mi = 0; mi < 2; ++mi) {
;     float l = lsum[mi]; l += shx(l, 16, lane); l += shx(l, 32, lane);
;     const float inv = 1.0f / l;
;     bf16_t* gp = projb + (size_t)(qg0 + 16 * mi) * NP + C_FG + fh * 64 + 4 * fq;
; #pragma unroll
;     for (int d = 0; d < 4; ++d) {
;       const uint2 gv = *(const uint2*)(gp + 16 * d);
;       uint2 w;
;       w.x = pk2(o[mi][d][0] * inv * silu_f(bflo(gv.x)), o[mi][d][1] * inv * silu_f(bfhi(gv.x)));
;       w.y = pk2(o[mi][d][2] * inv * silu_f(bflo(gv.y)), o[mi][d][3] * inv * silu_f(bfhi(gv.y)));
;       if (!dry || inv == 1.2345e-30f) *(uint2*)(gp + 16 * d) = w;
;     }
;   }
	v_add_f32_e32 v2, v129, v2
	ds_bpermute_b32 v3, v169, v2
	s_waitcnt lgkmcnt(0)
	v_add_f32_e32 v2, v2, v3
	v_div_scale_f32 v3, s[0:1], v2, v2, 1.0
	v_rcp_f32_e32 v4, v3
	s_nop 0
	v_fma_f32 v5, -v3, v4, 1.0
	v_fmac_f32_e32 v4, v5, v4
	v_div_scale_f32 v5, vcc, 1.0, v2, 1.0
	v_mul_f32_e32 v6, v5, v4
	v_fma_f32 v7, -v3, v6, v5
	v_fmac_f32_e32 v6, v7, v4
	v_fma_f32 v3, -v3, v6, v5
	v_div_fmas_f32 v3, v3, v4, v6
	v_div_fixup_f32 v4, v3, v2, 1.0
	v_lshl_add_u64 v[2:3], v[108:109], 0, s[2:3]
	v_lshl_add_u64 v[2:3], v[2:3], 0, v[0:1]
	v_lshl_add_u64 v[0:1], v[2:3], 0, s[6:7]
	v_add_co_u32_e32 v2, vcc, s4, v2
	v_mul_f32_e32 v5, v122, v4
	s_nop 0
	v_addc_co_u32_e32 v3, vcc, 0, v3, vcc
	global_load_dwordx2 v[6:7], v[2:3], off
	s_waitcnt vmcnt(0)
	v_lshlrev_b32_e32 v8, 16, v6
	v_mul_f32_e32 v9, 0xbfb8aa3b, v8
	v_exp_f32_e32 v9, v9
	v_and_b32_e32 v6, 0xffff0000, v6
	v_add_f32_e32 v9, 1.0, v9
	v_rcp_f32_e32 v9, v9
	s_nop 0
	v_mul_f32_e32 v8, v9, v8
	v_mul_f32_e32 v9, 0xbfb8aa3b, v6
	v_exp_f32_e32 v9, v9
	v_mul_f32_e32 v5, v5, v8
	v_mul_f32_e32 v8, v123, v4
	v_add_f32_e32 v9, 1.0, v9
	v_rcp_f32_e32 v9, v9
	s_nop 0
	v_mul_f32_e32 v6, v9, v6
	v_mul_f32_e32 v6, v8, v6
	v_lshlrev_b32_e32 v8, 16, v7
	v_mul_f32_e32 v9, 0xbfb8aa3b, v8
	v_exp_f32_e32 v9, v9
	v_and_b32_e32 v7, 0xffff0000, v7
	v_cvt_pk_bf16_f32 v6, v5, v6
	v_mul_f32_e32 v5, v124, v4
	v_add_f32_e32 v9, 1.0, v9
	v_rcp_f32_e32 v9, v9
	s_nop 0
	v_mul_f32_e32 v8, v9, v8
	v_mul_f32_e32 v9, 0xbfb8aa3b, v7
	v_exp_f32_e32 v9, v9
	v_mul_f32_e32 v5, v5, v8
	v_mul_f32_e32 v8, v125, v4
	v_add_f32_e32 v9, 1.0, v9
	v_rcp_f32_e32 v9, v9
	s_nop 0
	v_mul_f32_e32 v7, v9, v7
	v_mul_f32_e32 v7, v8, v7
	v_cvt_pk_bf16_f32 v7, v5, v7
	global_store_dwordx2 v[2:3], v[6:7], off
	global_load_dwordx2 v[2:3], v[0:1], off offset:32
	v_mul_f32_e32 v5, v118, v4
	s_waitcnt vmcnt(0)
	v_lshlrev_b32_e32 v6, 16, v2
	v_mul_f32_e32 v7, 0xbfb8aa3b, v6
	v_exp_f32_e32 v7, v7
	v_and_b32_e32 v2, 0xffff0000, v2
	v_add_f32_e32 v7, 1.0, v7
	v_rcp_f32_e32 v7, v7
	s_nop 0
	v_mul_f32_e32 v6, v7, v6
	v_mul_f32_e32 v7, 0xbfb8aa3b, v2
	v_exp_f32_e32 v7, v7
	v_mul_f32_e32 v5, v5, v6
	v_mul_f32_e32 v6, v119, v4
	v_add_f32_e32 v7, 1.0, v7
	v_rcp_f32_e32 v7, v7
	s_nop 0
	v_mul_f32_e32 v2, v7, v2
	v_mul_f32_e32 v2, v6, v2
	v_lshlrev_b32_e32 v6, 16, v3
	v_mul_f32_e32 v7, 0xbfb8aa3b, v6
	v_exp_f32_e32 v7, v7
	v_and_b32_e32 v3, 0xffff0000, v3
	v_cvt_pk_bf16_f32 v2, v5, v2
	v_mul_f32_e32 v5, v120, v4
	v_add_f32_e32 v7, 1.0, v7
	v_rcp_f32_e32 v7, v7
	s_nop 0
	v_mul_f32_e32 v6, v7, v6
	v_mul_f32_e32 v7, 0xbfb8aa3b, v3
	v_exp_f32_e32 v7, v7
	v_mul_f32_e32 v5, v5, v6
	v_mul_f32_e32 v6, v121, v4
	v_add_f32_e32 v7, 1.0, v7
	v_rcp_f32_e32 v7, v7
	s_nop 0
	v_mul_f32_e32 v3, v7, v3
	v_mul_f32_e32 v3, v6, v3
	v_cvt_pk_bf16_f32 v3, v5, v3
	global_store_dwordx2 v[0:1], v[2:3], off offset:32
	global_load_dwordx2 v[2:3], v[0:1], off offset:64
	v_mul_f32_e32 v5, v114, v4
	s_waitcnt vmcnt(0)
	v_lshlrev_b32_e32 v6, 16, v2
	v_mul_f32_e32 v7, 0xbfb8aa3b, v6
	v_exp_f32_e32 v7, v7
	v_and_b32_e32 v2, 0xffff0000, v2
	v_add_f32_e32 v7, 1.0, v7
	v_rcp_f32_e32 v7, v7
	s_nop 0
	v_mul_f32_e32 v6, v7, v6
	v_mul_f32_e32 v7, 0xbfb8aa3b, v2
	v_exp_f32_e32 v7, v7
	v_mul_f32_e32 v5, v5, v6
	v_mul_f32_e32 v6, v115, v4
	v_add_f32_e32 v7, 1.0, v7
	v_rcp_f32_e32 v7, v7
	s_nop 0
	v_mul_f32_e32 v2, v7, v2
	v_mul_f32_e32 v2, v6, v2
	v_lshlrev_b32_e32 v6, 16, v3
	v_mul_f32_e32 v7, 0xbfb8aa3b, v6
	v_exp_f32_e32 v7, v7
	v_and_b32_e32 v3, 0xffff0000, v3
	v_cvt_pk_bf16_f32 v2, v5, v2
	v_mul_f32_e32 v5, v116, v4
	v_add_f32_e32 v7, 1.0, v7
	v_rcp_f32_e32 v7, v7
	s_nop 0
	v_mul_f32_e32 v6, v7, v6
	v_mul_f32_e32 v7, 0xbfb8aa3b, v3
	v_exp_f32_e32 v7, v7
	v_mul_f32_e32 v5, v5, v6
	v_mul_f32_e32 v6, v117, v4
	v_add_f32_e32 v7, 1.0, v7
	v_rcp_f32_e32 v7, v7
	s_nop 0
	v_mul_f32_e32 v3, v7, v3
	v_mul_f32_e32 v3, v6, v3
	v_cvt_pk_bf16_f32 v3, v5, v3
	global_store_dwordx2 v[0:1], v[2:3], off offset:64
	global_load_dwordx2 v[2:3], v[0:1], off offset:96
	v_mul_f32_e32 v5, v110, v4
	s_waitcnt vmcnt(0)
	v_lshlrev_b32_e32 v6, 16, v2
	v_mul_f32_e32 v7, 0xbfb8aa3b, v6
	v_exp_f32_e32 v7, v7
	v_and_b32_e32 v2, 0xffff0000, v2
	v_add_f32_e32 v7, 1.0, v7
	v_rcp_f32_e32 v7, v7
	s_nop 0
	v_mul_f32_e32 v6, v7, v6
	v_mul_f32_e32 v7, 0xbfb8aa3b, v2
	v_exp_f32_e32 v7, v7
	v_mul_f32_e32 v5, v5, v6
	v_mul_f32_e32 v6, v111, v4
	v_add_f32_e32 v7, 1.0, v7
	v_rcp_f32_e32 v7, v7
	s_nop 0
	v_mul_f32_e32 v2, v7, v2
	v_mul_f32_e32 v2, v6, v2
	v_lshlrev_b32_e32 v6, 16, v3
	v_mul_f32_e32 v7, 0xbfb8aa3b, v6
	v_exp_f32_e32 v7, v7
	v_cvt_pk_bf16_f32 v2, v5, v2
	v_mul_f32_e32 v5, v112, v4
	v_and_b32_e32 v3, 0xffff0000, v3
	v_add_f32_e32 v7, 1.0, v7
	v_rcp_f32_e32 v7, v7
	v_mul_f32_e32 v4, v113, v4
	v_mul_f32_e32 v6, v7, v6
	v_mul_f32_e32 v5, v5, v6
	v_mul_f32_e32 v6, 0xbfb8aa3b, v3
	v_exp_f32_e32 v6, v6
	s_nop 0
	v_add_f32_e32 v6, 1.0, v6
	v_rcp_f32_e32 v6, v6
	s_nop 0
	v_mul_f32_e32 v3, v6, v3
	v_mul_f32_e32 v3, v4, v3
	v_cvt_pk_bf16_f32 v3, v5, v3
	global_store_dwordx2 v[0:1], v[2:3], off offset:96
	s_cbranch_execz .LBB0_501
	v_mov_b32_e32 v162, 0x358637bd
	v_mov_b32_e32 v168, 0x3f317218
	v_mov_b64_e32 v[170:171], 0xff
	v_mov_b32_e32 v195, 0x3ecc95a3
	v_mov_b64_e32 v[196:197], 0x6bf
	v_mov_b32_e32 v198, 0x7f800000
	v_mov_b32_e32 v199, 0x7fc00000
	s_branch .LBB0_572
